# de-serialized epilogue load/store chains (gate/ffup img_load, resid RMW, gla3 gate loads, cache V transpose) and spread sample tiles over workgroups
# speedup vs baseline: 1.0533x; 1.0533x over previous
; DI bool xcd_tile(int B, int G, int iter, int MTILES, int NT, int& mt, int& nt) {
;   const int nxb = G >> 3;
;   const int x = B & 7, lb = B >> 3;
;   const int q = MTILES >> 3, r = MTILES & 7;
;   const int mx = q + (x < r ? 1 : 0);
;   const int mbase = x * q + (x < r ? x : r);
;   const int j = lb + iter * nxb;
;   if (j >= mx * NT) return false;
;   const int band = j / (8 * NT);
;   const int rem = j - band * 8 * NT;
;   const int nb = (mx - band * 8) < 8 ? (mx - band * 8) : 8;
;   mt = mbase + band * 8 + rem % nb;
;   nt = rem / nb;
;   return true;
; }
.LBB0_136:
	s_mul_i32 s6, s28, s33
	s_add_i32 s6, s6, s16
	v_readlane_b32 s7, v252, 26
	s_cmp_lt_i32 s6, s7
	s_cselect_b64 s[4:5], -1, 0
	s_cmp_ge_i32 s6, s7
	s_cbranch_scc1 .LBB0_138
	s_ashr_i32 s7, s6, 31
	s_lshr_b32 s7, s7, 25
	s_add_i32 s7, s6, s7
	s_ashr_i32 s8, s7, 7
	s_lshl_b32 s8, s8, 3
	v_readlane_b32 s9, v253, 52
	s_sub_i32 s9, s9, s8
	s_min_u32 s9, s9, 8
	v_cvt_f32_ubyte0_e32 v0, s9
	v_rcp_iflag_f32_e32 v0, v0
	s_sub_i32 s13, 0, s9
	s_and_b32 s7, s7, 0xffffff80
	s_sub_i32 s6, s6, s7
	v_mul_f32_e32 v0, 0x4f7ffffe, v0
	v_cvt_u32_f32_e32 v0, v0
	s_abs_i32 s12, s6
	v_readlane_b32 s7, v252, 25
	s_add_i32 s7, s7, s8
	v_readfirstlane_b32 s15, v0
	s_mul_i32 s13, s13, s15
	s_mul_hi_u32 s13, s15, s13
	s_add_i32 s15, s15, s13
	s_mul_hi_u32 s13, s12, s15
	s_mul_i32 s15, s13, s9
	s_sub_i32 s12, s12, s15
	s_ashr_i32 s8, s6, 31
	s_add_i32 s15, s13, 1
	s_sub_i32 s20, s12, s9
	s_cmp_ge_u32 s12, s9
	s_cselect_b32 s13, s15, s13
	s_cselect_b32 s12, s20, s12
	s_add_i32 s15, s13, 1
	s_cmp_ge_u32 s12, s9
	s_cselect_b32 s12, s15, s13
	s_xor_b32 s12, s12, s8
	s_sub_i32 s15, s12, s8
	s_mul_i32 s8, s15, s9
	s_sub_i32 s6, s6, s8
	s_lshl_b32 s12, s28, 1
	s_add_i32 s12, s12, s6
	s_and_b32 s12, s12, 7
	s_cmp_eq_u32 s9, 8
	s_cselect_b32 s6, s12, s6
	s_add_i32 s6, s7, s6
	v_writelane_b32 v254, s6, 59
	s_mov_b64 s[6:7], -1
	s_and_b64 vcc, exec, s[4:5]
	s_cbranch_vccz .LBB0_135
	s_branch .LBB0_139

; DI int TID() { int t = threadIdx.x & 255; asm volatile("" : "+v"(t)); return t; }
; DI void transpose_tile(const float* src, int lds_, int k0, int c0, int ncols_valid, u16* dst, int ldd, int n0, float* tile) {
;   const int tid = TID();
;   __syncthreads();
; #pragma unroll
;   for (int i = 0; i < 16; ++i) {
;     int e = tid + i * 256, r = e >> 6, c = e & 63;
;     tile[r * 65 + c] = (c < ncols_valid) ? __builtin_nontemporal_load(&src[(size_t)(k0 + r) * lds_ + c0 + c]) : 0.f;
;   }
;   __syncthreads();
; DI void cache_conv_item(const Params& p, int l, int it, char* smem) {
;     ...
;   it -= PB_KC;
;   const int b = it / 256, r = it % 256, ptile = r / 8, ctile = r % 8;
;   const float* src = p.in[3] + ((size_t)l * SBT + b) * PAST * 512;
;   u16* VTS = (u16*)(p.ws + O_VTS);
;   transpose_tile(src, 512, ptile * 64, ctile * 64, 64, VTS + (size_t)b * 512 * SKP, SKP, ctile * 64, (float*)smem);
.LBB0_1255:
	s_movk_i32 s10, 0xfff
	v_mov_b32_e32 v6, v184
	v_mov_b32_e32 v8, v185
	v_cmp_lt_i32_e32 vcc, s10, v2
	s_and_saveexec_b64 s[10:11], vcc
	s_xor_b64 s[12:13], exec, s[10:11]
	s_cbranch_execz .LBB0_1257
	v_lshrrev_b32_e32 v6, 8, v6
	s_mov_b32 s10, 0x12000
	v_mad_i32_i24 v22, v6, s10, 16
	v_add_u32_e32 v6, 0xfffff000, v2
	v_lshrrev_b32_e32 v172, 8, v6
	v_readlane_b32 s10, v252, 49
	v_lshlrev_b64 v[6:7], 22, v[172:173]
	v_readlane_b32 s11, v252, 50
	v_mov_b32_e32 v13, v185
	v_lshl_add_u64 v[8:9], s[6:7], 0, v[6:7]
	v_and_b32_e32 v23, 0x7c0, v10
	v_and_b32_e32 v12, 0x1c0, v11
	v_mov_b64_e32 v[6:7], s[10:11]
	s_mov_b32 s10, 0x210000
	v_mad_u64_u32 v[6:7], s[10:11], v172, s10, v[6:7]
	v_ashrrev_i32_e32 v24, 6, v13
	v_and_b32_e32 v31, 63, v13
	v_lshlrev_b32_e32 v172, 2, v12
	v_add_u32_e32 v14, v24, v23
	v_lshl_add_u64 v[8:9], v[8:9], 0, v[172:173]
	v_lshlrev_b32_e32 v172, 2, v31
	v_ashrrev_i32_e32 v15, 31, v14
	v_lshl_add_u64 v[8:9], v[8:9], 0, v[172:173]
	v_lshlrev_b64 v[14:15], 11, v[14:15]
	v_lshl_add_u64 v[14:15], v[8:9], 0, v[14:15]
	s_waitcnt vmcnt(0)
	s_barrier
	global_load_dword v40, v[14:15], off nt
	s_movk_i32 s10, 0x104
	v_mul_lo_u32 v56, v24, s10
	v_add3_u32 v56, v22, v56, v172
	v_add_u32_e32 v14, 0x100, v13
	v_ashrrev_i32_e32 v25, 6, v14
	v_add_u32_e32 v14, v25, v23
	v_ashrrev_i32_e32 v15, 31, v14
	v_lshlrev_b64 v[14:15], 11, v[14:15]
	v_lshl_add_u64 v[14:15], v[8:9], 0, v[14:15]
	global_load_dword v41, v[14:15], off nt
	v_mul_lo_u32 v57, v25, s10
	v_add3_u32 v57, v22, v57, v172
	v_add_u32_e32 v14, 0x200, v13
	v_ashrrev_i32_e32 v26, 6, v14
	v_add_u32_e32 v14, v26, v23
	v_ashrrev_i32_e32 v15, 31, v14
	v_lshlrev_b64 v[14:15], 11, v[14:15]
	v_lshl_add_u64 v[14:15], v[8:9], 0, v[14:15]
	global_load_dword v42, v[14:15], off nt
	v_mul_lo_u32 v58, v26, s10
	v_add3_u32 v58, v22, v58, v172
	v_add_u32_e32 v14, 0x300, v13
	v_ashrrev_i32_e32 v27, 6, v14
	v_add_u32_e32 v14, v27, v23
	v_ashrrev_i32_e32 v15, 31, v14
	v_lshlrev_b64 v[14:15], 11, v[14:15]
	v_lshl_add_u64 v[14:15], v[8:9], 0, v[14:15]
	global_load_dword v43, v[14:15], off nt
	v_mul_lo_u32 v59, v27, s10
	v_add3_u32 v59, v22, v59, v172
	v_add_u32_e32 v14, 0x400, v13
	v_ashrrev_i32_e32 v28, 6, v14
	v_add_u32_e32 v14, v28, v23
	v_ashrrev_i32_e32 v15, 31, v14
	v_lshlrev_b64 v[14:15], 11, v[14:15]
	v_lshl_add_u64 v[14:15], v[8:9], 0, v[14:15]
	global_load_dword v44, v[14:15], off nt
	v_mul_lo_u32 v60, v28, s10
	v_add3_u32 v60, v22, v60, v172
	v_add_u32_e32 v14, 0x500, v13
	v_ashrrev_i32_e32 v29, 6, v14
	v_add_u32_e32 v14, v29, v23
	v_ashrrev_i32_e32 v15, 31, v14
	v_lshlrev_b64 v[14:15], 11, v[14:15]
	v_lshl_add_u64 v[14:15], v[8:9], 0, v[14:15]
	global_load_dword v45, v[14:15], off nt
	v_mul_lo_u32 v61, v29, s10
	v_add3_u32 v61, v22, v61, v172
	v_add_u32_e32 v14, 0x600, v13
	v_ashrrev_i32_e32 v30, 6, v14
	v_add_u32_e32 v14, v30, v23
	v_ashrrev_i32_e32 v15, 31, v14
	v_lshlrev_b64 v[14:15], 11, v[14:15]
	v_lshl_add_u64 v[14:15], v[8:9], 0, v[14:15]
	global_load_dword v46, v[14:15], off nt
	v_mul_lo_u32 v62, v30, s10
	v_add3_u32 v62, v22, v62, v172
	v_add_u32_e32 v14, 0x700, v13
	v_ashrrev_i32_e32 v14, 6, v14
	v_add_u32_e32 v16, v14, v23
	v_ashrrev_i32_e32 v17, 31, v16
	v_lshlrev_b64 v[16:17], 11, v[16:17]
	v_lshl_add_u64 v[16:17], v[8:9], 0, v[16:17]
	global_load_dword v47, v[16:17], off nt
	v_mul_lo_u32 v63, v14, s10
	v_add3_u32 v63, v22, v63, v172
	v_add_u32_e32 v15, 0x800, v13
	v_ashrrev_i32_e32 v15, 6, v15
	v_add_u32_e32 v16, v15, v23
	v_ashrrev_i32_e32 v17, 31, v16
	v_lshlrev_b64 v[16:17], 11, v[16:17]
	v_lshl_add_u64 v[16:17], v[8:9], 0, v[16:17]
	global_load_dword v48, v[16:17], off nt
	v_mul_lo_u32 v64, v15, s10
	v_add3_u32 v64, v22, v64, v172
	v_add_u32_e32 v16, 0x900, v13
	v_ashrrev_i32_e32 v16, 6, v16
	v_add_u32_e32 v18, v16, v23
	v_ashrrev_i32_e32 v19, 31, v18
	v_lshlrev_b64 v[18:19], 11, v[18:19]
	v_lshl_add_u64 v[18:19], v[8:9], 0, v[18:19]
	global_load_dword v49, v[18:19], off nt
	v_mul_lo_u32 v65, v16, s10
	v_add3_u32 v65, v22, v65, v172
	v_add_u32_e32 v17, 0xa00, v13
	v_ashrrev_i32_e32 v17, 6, v17
	v_add_u32_e32 v18, v17, v23
	v_ashrrev_i32_e32 v19, 31, v18
	v_lshlrev_b64 v[18:19], 11, v[18:19]
	v_lshl_add_u64 v[18:19], v[8:9], 0, v[18:19]
	global_load_dword v50, v[18:19], off nt
	v_mul_lo_u32 v66, v17, s10
	v_add3_u32 v66, v22, v66, v172
	v_add_u32_e32 v18, 0xb00, v13
	v_ashrrev_i32_e32 v18, 6, v18
	v_add_u32_e32 v20, v18, v23
	v_ashrrev_i32_e32 v21, 31, v20
	v_lshlrev_b64 v[20:21], 11, v[20:21]
	v_lshl_add_u64 v[20:21], v[8:9], 0, v[20:21]
	global_load_dword v51, v[20:21], off nt
	v_mul_lo_u32 v67, v18, s10
	v_add3_u32 v67, v22, v67, v172
	v_add_u32_e32 v19, 0xc00, v13
	v_ashrrev_i32_e32 v19, 6, v19
	v_add_u32_e32 v20, v19, v23
	v_ashrrev_i32_e32 v21, 31, v20
	v_lshlrev_b64 v[20:21], 11, v[20:21]
	v_lshl_add_u64 v[20:21], v[8:9], 0, v[20:21]
	global_load_dword v52, v[20:21], off nt
	v_mul_lo_u32 v68, v19, s10
	v_add3_u32 v68, v22, v68, v172
	v_add_u32_e32 v20, 0xd00, v13
	v_ashrrev_i32_e32 v20, 6, v20
	v_add_u32_e32 v32, v20, v23
	v_ashrrev_i32_e32 v33, 31, v32
	v_lshlrev_b64 v[32:33], 11, v[32:33]
	v_lshl_add_u64 v[32:33], v[8:9], 0, v[32:33]
	global_load_dword v53, v[32:33], off nt
	v_mul_lo_u32 v69, v20, s10
	v_add3_u32 v69, v22, v69, v172
	v_add_u32_e32 v21, 0xe00, v13
	v_ashrrev_i32_e32 v21, 6, v21
	v_add_u32_e32 v32, v21, v23
	v_ashrrev_i32_e32 v33, 31, v32
	v_lshlrev_b64 v[32:33], 11, v[32:33]
	v_lshl_add_u64 v[32:33], v[8:9], 0, v[32:33]
	global_load_dword v54, v[32:33], off nt
	v_mul_lo_u32 v70, v21, s10
	v_add_u32_e32 v13, 0xf00, v13
	v_add3_u32 v70, v22, v70, v172
	v_ashrrev_i32_e32 v13, 6, v13
	v_add_u32_e32 v32, v13, v23
	v_ashrrev_i32_e32 v33, 31, v32
	v_lshlrev_b64 v[32:33], 11, v[32:33]
	v_lshl_add_u64 v[8:9], v[8:9], 0, v[32:33]
	global_load_dword v55, v[8:9], off nt
	v_mul_lo_u32 v71, v13, s10
	v_add3_u32 v71, v22, v71, v172
	v_lshlrev_b32_e32 v172, 1, v23
	v_lshl_add_u64 v[6:7], v[6:7], 0, v[172:173]
	v_lshlrev_b32_e32 v172, 1, v31
	v_lshl_add_u64 v[6:7], v[6:7], 0, v[172:173]
	v_mul_u32_u24_e32 v8, 0x41, v31
	v_lshl_add_u32 v22, v8, 2, v22
	v_lshl_add_u32 v8, v24, 2, v22
	s_waitcnt vmcnt(15)
	ds_write_b32 v56, v40
	s_waitcnt vmcnt(14)
	ds_write_b32 v57, v41
	s_waitcnt vmcnt(13)
	ds_write_b32 v58, v42
	s_waitcnt vmcnt(12)
	ds_write_b32 v59, v43
	s_waitcnt vmcnt(11)
	ds_write_b32 v60, v44
	s_waitcnt vmcnt(10)
	ds_write_b32 v61, v45
	s_waitcnt vmcnt(9)
	ds_write_b32 v62, v46
	s_waitcnt vmcnt(8)
	ds_write_b32 v63, v47
	s_waitcnt vmcnt(7)
	ds_write_b32 v64, v48
	s_waitcnt vmcnt(6)
	ds_write_b32 v65, v49
	s_waitcnt vmcnt(5)
	ds_write_b32 v66, v50
	s_waitcnt vmcnt(4)
	ds_write_b32 v67, v51
	s_waitcnt vmcnt(3)
	ds_write_b32 v68, v52
	s_waitcnt vmcnt(2)
	ds_write_b32 v69, v53
	s_waitcnt vmcnt(1)
	ds_write_b32 v70, v54
	s_waitcnt vmcnt(0)
	ds_write_b32 v71, v55
	s_waitcnt lgkmcnt(0)
	s_barrier
; DI void transpose_tile(const float* src, int lds_, int k0, int c0, int ncols_valid, u16* dst, int ldd, int n0, float* tile) {
;     ...
; #pragma unroll
;   for (int i = 0; i < 16; ++i) {
;     int e = tid + i * 256, c = e >> 6, r = e & 63;
;     dst[(size_t)(n0 + c) * ldd + k0 + r] = f2bf(tile[r * 65 + c]);
;   }
	ds_read_b32 v8, v8
	s_waitcnt lgkmcnt(0)
	v_cvt_pk_bf16_f32 v23, v8, s0
	v_add_u32_e32 v8, v24, v12
	v_mad_i64_i32 v[8:9], s[10:11], v8, s2, v[6:7]
	global_store_short v[8:9], v23, off
	v_lshl_add_u32 v8, v25, 2, v22
	ds_read_b32 v8, v8
	s_waitcnt lgkmcnt(0)
	v_cvt_pk_bf16_f32 v23, v8, s0
	v_add_u32_e32 v8, v25, v12
	v_mad_i64_i32 v[8:9], s[10:11], v8, s2, v[6:7]
	global_store_short v[8:9], v23, off
	v_lshl_add_u32 v8, v26, 2, v22
	ds_read_b32 v8, v8
	s_waitcnt lgkmcnt(0)
	v_cvt_pk_bf16_f32 v23, v8, s0
	v_add_u32_e32 v8, v26, v12
	v_mad_i64_i32 v[8:9], s[10:11], v8, s2, v[6:7]
	global_store_short v[8:9], v23, off
	v_lshl_add_u32 v8, v27, 2, v22
	ds_read_b32 v8, v8
	s_waitcnt lgkmcnt(0)
	v_cvt_pk_bf16_f32 v23, v8, s0
	v_add_u32_e32 v8, v27, v12
	v_mad_i64_i32 v[8:9], s[10:11], v8, s2, v[6:7]
	global_store_short v[8:9], v23, off
	v_lshl_add_u32 v8, v28, 2, v22
	ds_read_b32 v8, v8
	s_waitcnt lgkmcnt(0)
	v_cvt_pk_bf16_f32 v23, v8, s0
	v_add_u32_e32 v8, v28, v12
	v_mad_i64_i32 v[8:9], s[10:11], v8, s2, v[6:7]
	global_store_short v[8:9], v23, off
	v_lshl_add_u32 v8, v29, 2, v22
	ds_read_b32 v8, v8
	s_waitcnt lgkmcnt(0)
	v_cvt_pk_bf16_f32 v23, v8, s0
	v_add_u32_e32 v8, v29, v12
	v_mad_i64_i32 v[8:9], s[10:11], v8, s2, v[6:7]
	global_store_short v[8:9], v23, off
	v_lshl_add_u32 v8, v30, 2, v22
	ds_read_b32 v8, v8
	s_waitcnt lgkmcnt(0)
	v_cvt_pk_bf16_f32 v23, v8, s0
	v_add_u32_e32 v8, v30, v12
	v_mad_i64_i32 v[8:9], s[10:11], v8, s2, v[6:7]
	global_store_short v[8:9], v23, off
	v_lshl_add_u32 v8, v14, 2, v22
	ds_read_b32 v8, v8
	s_waitcnt lgkmcnt(0)
	v_cvt_pk_bf16_f32 v23, v8, s0
	v_add_u32_e32 v8, v14, v12
	v_mad_i64_i32 v[8:9], s[10:11], v8, s2, v[6:7]
	global_store_short v[8:9], v23, off
	v_lshl_add_u32 v8, v15, 2, v22
	ds_read_b32 v8, v8
	s_waitcnt lgkmcnt(0)
	v_cvt_pk_bf16_f32 v14, v8, s0
	v_add_u32_e32 v8, v15, v12
	v_mad_i64_i32 v[8:9], s[10:11], v8, s2, v[6:7]
	global_store_short v[8:9], v14, off
	v_lshl_add_u32 v8, v16, 2, v22
	ds_read_b32 v8, v8
	s_waitcnt lgkmcnt(0)
	v_cvt_pk_bf16_f32 v14, v8, s0
	v_add_u32_e32 v8, v16, v12
	v_mad_i64_i32 v[8:9], s[10:11], v8, s2, v[6:7]
	global_store_short v[8:9], v14, off
	v_lshl_add_u32 v8, v17, 2, v22
	ds_read_b32 v8, v8
	s_waitcnt lgkmcnt(0)
	v_cvt_pk_bf16_f32 v14, v8, s0
	v_add_u32_e32 v8, v17, v12
	v_mad_i64_i32 v[8:9], s[10:11], v8, s2, v[6:7]
	global_store_short v[8:9], v14, off
	v_lshl_add_u32 v8, v18, 2, v22
	ds_read_b32 v8, v8
	s_waitcnt lgkmcnt(0)
	v_cvt_pk_bf16_f32 v14, v8, s0
	v_add_u32_e32 v8, v18, v12
	v_mad_i64_i32 v[8:9], s[10:11], v8, s2, v[6:7]
	global_store_short v[8:9], v14, off
	v_lshl_add_u32 v8, v19, 2, v22
	ds_read_b32 v8, v8
	s_waitcnt lgkmcnt(0)
	v_cvt_pk_bf16_f32 v14, v8, s0
	v_add_u32_e32 v8, v19, v12
	v_mad_i64_i32 v[8:9], s[10:11], v8, s2, v[6:7]
	global_store_short v[8:9], v14, off
	v_lshl_add_u32 v8, v20, 2, v22
	ds_read_b32 v8, v8
	s_waitcnt lgkmcnt(0)
	v_cvt_pk_bf16_f32 v14, v8, s0
	v_add_u32_e32 v8, v20, v12
	v_mad_i64_i32 v[8:9], s[10:11], v8, s2, v[6:7]
	global_store_short v[8:9], v14, off
	v_lshl_add_u32 v8, v21, 2, v22
	ds_read_b32 v8, v8
	s_waitcnt lgkmcnt(0)
	v_cvt_pk_bf16_f32 v14, v8, s0
	v_add_u32_e32 v8, v21, v12
	v_mad_i64_i32 v[8:9], s[10:11], v8, s2, v[6:7]
	global_store_short v[8:9], v14, off
	v_lshl_add_u32 v8, v13, 2, v22
	ds_read_b32 v8, v8
	v_add_u32_e32 v9, v13, v12
	v_mad_i64_i32 v[6:7], s[10:11], v9, s2, v[6:7]
	s_waitcnt lgkmcnt(0)
	v_cvt_pk_bf16_f32 v8, v8, s0
	global_store_short v[6:7], v8, off

; DI void gla_load_vt(const Params& p, int row0, int Lc, int h, u16* vt) {
;     ...
; #pragma unroll
;   for (int i = 0; i < 4; ++i) {
;     const int vd0 = (cg4 + 4 * i) * 8;
; #pragma unroll
;     for (int e = 0; e < 4; ++e) {
;       vt[(vd0 + 2 * e) * LP + s] = (u16)(v[i][e] & 0xffffu);
;       vt[(vd0 + 2 * e + 1) * LP + s] = (u16)(v[i][e] >> 16);
;     }
;   }
; DI void gla3_item(const Params& p, int l, int gi, char* smem) {
;     ...
;   gla_load_vt(p, row0, Lc, h, vt);
;   __syncthreads();
;   {
;     f32x4 a[4];
; #pragma unroll
;     for (int n = 0; n < 4; ++n) a[n] = lds_mm<2>(qt, LP, wid * 16, kt_, LP, n * 16, f32x4{0.f, 0.f, 0.f, 0.f});
; #pragma unroll
;     for (int n = 0; n < 4; ++n)
; #pragma unroll
;       for (int j = 0; j < 4; ++j) {
;         const int t = wid * 16 + fq * 4 + j, s = n * 16 + fr;
;         att[t * LP + s] = f2bf(t >= s ? a[n][j] : 0.f);
;       }
;   }
.LBB0_1898:
	s_or_b64 exec, exec, s[4:5]
	v_mul_lo_u32 v20, v20, s70
	v_lshlrev_b32_e32 v21, 1, v24
	v_add3_u32 v20, v45, v20, v21
	s_waitcnt vmcnt(0)
	ds_write_b16 v20, v8 offset:36864
	ds_write_b16_d16_hi v20, v8 offset:37008
	ds_write_b16 v20, v9 offset:37152
	ds_write_b16_d16_hi v20, v9 offset:37296
	ds_write_b16 v20, v10 offset:37440
	ds_write_b16_d16_hi v20, v10 offset:37584
	ds_write_b16 v20, v11 offset:37728
	ds_write_b16_d16_hi v20, v11 offset:37872
	ds_write_b16 v20, v4 offset:41472
	ds_write_b16_d16_hi v20, v4 offset:41616
	ds_write_b16 v20, v5 offset:41760
	ds_write_b16_d16_hi v20, v5 offset:41904
	ds_write_b16 v20, v6 offset:42048
	ds_write_b16_d16_hi v20, v6 offset:42192
	ds_write_b16 v20, v7 offset:42336
	ds_write_b16_d16_hi v20, v7 offset:42480
	ds_write_b16 v20, v16 offset:46080
	ds_write_b16_d16_hi v20, v16 offset:46224
	ds_write_b16 v20, v17 offset:46368
	ds_write_b16_d16_hi v20, v17 offset:46512
	ds_write_b16 v20, v18 offset:46656
	ds_write_b16_d16_hi v20, v18 offset:46800
	ds_write_b16 v20, v19 offset:46944
	ds_write_b16_d16_hi v20, v19 offset:47088
	ds_write_b16 v20, v12 offset:50688
	ds_write_b16_d16_hi v20, v12 offset:50832
	ds_write_b16 v20, v13 offset:50976
	ds_write_b16_d16_hi v20, v13 offset:51120
	ds_write_b16 v20, v14 offset:51264
	ds_write_b16_d16_hi v20, v14 offset:51408
	ds_write_b16 v20, v15 offset:51552
	ds_write_b16_d16_hi v20, v15 offset:51696
	v_mov_b32_e32 v4, v185
	s_waitcnt lgkmcnt(0)
	s_barrier
	v_lshlrev_b32_e32 v16, 4, v48
	v_and_b32_e32 v36, 15, v46
	v_and_b32_e32 v5, 15, v4
	v_or_b32_e32 v6, v5, v16
	v_mul_lo_u32 v6, v6, s70
	v_and_b32_e32 v4, 48, v4
	v_add3_u32 v12, v45, v6, v4
	v_mul_u32_u24_e32 v5, 0x90, v5
	v_add3_u32 v13, v45, v5, v4
	ds_read_b128 v[4:7], v12 offset:18432
	ds_read_b128 v[8:11], v13 offset:27648
	s_waitcnt lgkmcnt(0)
	v_mfma_f32_16x16x32_bf16 v[4:7], v[4:7], v[8:11], 0
	ds_read_b128 v[8:11], v12 offset:18496
	ds_read_b128 v[12:15], v13 offset:27712
	v_lshlrev_b32_e32 v172, 1, v36
	v_lshlrev_b32_e32 v1, 7, v47
	s_waitcnt lgkmcnt(0)
	v_mfma_f32_16x16x32_bf16 v[4:7], v[8:11], v[12:15], v[4:7]
	v_mov_b32_e32 v8, v185
	s_mov_b32 s4, 0xd800
	v_and_b32_e32 v9, 15, v8
	v_or_b32_e32 v10, v9, v16
	v_mul_lo_u32 v10, v10, s70
	v_and_b32_e32 v8, 48, v8
	v_add3_u32 v17, v45, v10, v8
	v_mul_u32_u24_e32 v9, 0x90, v9
	v_add3_u32 v18, v45, v9, v8
	ds_read_b128 v[8:11], v17 offset:18432
	ds_read_b128 v[12:15], v18 offset:29952
	s_waitcnt lgkmcnt(0)
	v_mfma_f32_16x16x32_bf16 v[8:11], v[8:11], v[12:15], 0
	ds_read_b128 v[12:15], v17 offset:18496
	ds_read_b128 v[18:21], v18 offset:30016
	v_cvt_pk_bf16_f32 v4, v4, s0
	s_waitcnt lgkmcnt(0)
	v_mfma_f32_16x16x32_bf16 v[8:11], v[12:15], v[18:21], v[8:11]
	v_mov_b32_e32 v12, v185
	s_nop 0
	v_and_b32_e32 v13, 15, v12
	v_or_b32_e32 v14, v13, v16
	v_mul_lo_u32 v14, v14, s70
	v_and_b32_e32 v12, 48, v12
	v_add3_u32 v17, v45, v14, v12
	v_mul_u32_u24_e32 v13, 0x90, v13
	v_add3_u32 v22, v45, v13, v12
	ds_read_b128 v[12:15], v17 offset:18432
	ds_read_b128 v[18:21], v22 offset:32256
	s_waitcnt lgkmcnt(0)
	v_mfma_f32_16x16x32_bf16 v[12:15], v[12:15], v[18:21], 0
	ds_read_b128 v[18:21], v17 offset:18496
	ds_read_b128 v[22:25], v22 offset:32320
	v_mov_b32_e32 v17, v185
	s_waitcnt lgkmcnt(0)
	v_mfma_f32_16x16x32_bf16 v[12:15], v[18:21], v[22:25], v[12:15]
	v_and_b32_e32 v18, 15, v17
	v_or_b32_e32 v19, v18, v16
	v_mul_lo_u32 v19, v19, s70
	v_and_b32_e32 v17, 48, v17
	v_add3_u32 v26, v45, v19, v17
	v_mul_u32_u24_e32 v18, 0x90, v18
	v_add3_u32 v17, v45, v18, v17
	ds_read_b128 v[18:21], v26 offset:18432
	ds_read_b128 v[22:25], v17 offset:34560
	s_waitcnt lgkmcnt(0)
	v_mfma_f32_16x16x32_bf16 v[18:21], v[18:21], v[22:25], 0
	ds_read_b128 v[22:25], v26 offset:18496
	ds_read_b128 v[26:29], v17 offset:34624
	v_lshrrev_b32_e32 v17, 2, v46
	v_and_or_b32 v37, v17, 12, v16
	v_cmp_ge_i32_e32 vcc, v37, v36
	v_mul_lo_u32 v17, v37, s70
	v_add3_u32 v17, v45, v17, v172
	v_cndmask_b32_e32 v4, 0, v4, vcc
	v_or_b32_e32 v55, 1, v37
	ds_write_b16 v17, v4
	v_cvt_pk_bf16_f32 v4, v5, s0
	v_cmp_ge_i32_e32 vcc, v55, v36
	v_or_b32_e32 v54, 2, v37
	v_or_b32_e32 v40, 3, v37
	v_cndmask_b32_e32 v4, 0, v4, vcc
	ds_write_b16 v17, v4 offset:144
	v_cvt_pk_bf16_f32 v4, v6, s0
	v_cmp_ge_i32_e32 vcc, v54, v36
	v_cvt_pk_bf16_f32 v5, v8, s0
	s_waitcnt lgkmcnt(2)
	v_mfma_f32_16x16x32_bf16 v[18:21], v[22:25], v[26:29], v[18:21]
	v_cndmask_b32_e32 v4, 0, v4, vcc
	ds_write_b16 v17, v4 offset:288
	v_cvt_pk_bf16_f32 v4, v7, s0
	v_cmp_ge_i32_e32 vcc, v40, v36
	s_nop 1
	v_cndmask_b32_e32 v4, 0, v4, vcc
	ds_write_b16 v17, v4 offset:432
	v_or_b32_e32 v4, 16, v36
	v_cmp_ge_i32_e32 vcc, v37, v4
	s_nop 1
	v_cndmask_b32_e32 v5, 0, v5, vcc
	ds_write_b16 v17, v5 offset:32
	v_cvt_pk_bf16_f32 v5, v9, s0
	v_cmp_ge_i32_e32 vcc, v55, v4
	s_nop 1
	v_cndmask_b32_e32 v5, 0, v5, vcc
	ds_write_b16 v17, v5 offset:176
	v_cvt_pk_bf16_f32 v5, v10, s0
	v_cmp_ge_i32_e32 vcc, v54, v4
	s_nop 1
	v_cndmask_b32_e32 v5, 0, v5, vcc
	ds_write_b16 v17, v5 offset:320
	v_cvt_pk_bf16_f32 v5, v11, s0
	v_cmp_ge_i32_e32 vcc, v40, v4
	s_nop 1
	v_cndmask_b32_e32 v4, 0, v5, vcc
	ds_write_b16 v17, v4 offset:464
	v_or_b32_e32 v4, 32, v36
	v_cvt_pk_bf16_f32 v5, v12, s0
	v_cmp_ge_i32_e32 vcc, v37, v4
	s_nop 1
	v_cndmask_b32_e32 v5, 0, v5, vcc
	ds_write_b16 v17, v5 offset:64
	v_cvt_pk_bf16_f32 v5, v13, s0
	v_cmp_ge_i32_e32 vcc, v55, v4
	s_nop 1
	v_cndmask_b32_e32 v5, 0, v5, vcc
	ds_write_b16 v17, v5 offset:208
	v_cvt_pk_bf16_f32 v5, v14, s0
	v_cmp_ge_i32_e32 vcc, v54, v4
	s_nop 1
	v_cndmask_b32_e32 v5, 0, v5, vcc
	ds_write_b16 v17, v5 offset:352
	v_cvt_pk_bf16_f32 v5, v15, s0
	v_cmp_ge_i32_e32 vcc, v40, v4
	s_nop 1
	v_cndmask_b32_e32 v4, 0, v5, vcc
	ds_write_b16 v17, v4 offset:496
	v_or_b32_e32 v4, 48, v36
	v_cvt_pk_bf16_f32 v5, v18, s0
	v_cmp_ge_i32_e32 vcc, v37, v4
	v_lshlrev_b32_e32 v36, 2, v36
	s_nop 0
	v_cndmask_b32_e32 v5, 0, v5, vcc
	ds_write_b16 v17, v5 offset:96
	v_cvt_pk_bf16_f32 v5, v19, s0
	v_cmp_ge_i32_e32 vcc, v55, v4
	s_nop 1
	v_cndmask_b32_e32 v5, 0, v5, vcc
	ds_write_b16 v17, v5 offset:240
	v_cvt_pk_bf16_f32 v5, v20, s0
	v_cmp_ge_i32_e32 vcc, v54, v4
	s_nop 1
	v_cndmask_b32_e32 v5, 0, v5, vcc
	ds_write_b16 v17, v5 offset:384
	v_cvt_pk_bf16_f32 v5, v21, s0
	v_cmp_ge_i32_e32 vcc, v40, v4
	s_nop 1
	v_cndmask_b32_e32 v4, 0, v5, vcc
	ds_write_b16 v17, v4 offset:528
	v_mov_b32_e32 v4, v185
	s_waitcnt lgkmcnt(0)
	s_barrier
; DI void gla3_item(const Params& p, int l, int gi, char* smem) {
;     ...
;   f32x4 o[8];
; #pragma unroll
;   for (int n = 0; n < 8; ++n) {
;     f32x4 a = lds_mm<2>(att, LP, wid * 16, vt, LP, n * 16, f32x4{0.f, 0.f, 0.f, 0.f});
;     o[n] = lds_mm<2>(qt, LP, wid * 16, st, LP, n * 16, a);
;   }
	v_cmp_lt_i32_e32 vcc, v192, v191
	v_and_b32_e32 v5, 15, v4
	v_or_b32_e32 v6, v5, v16
	v_mul_lo_u32 v6, v6, s70
	v_and_b32_e32 v4, 48, v4
	v_add3_u32 v12, v45, v6, v4
	v_mul_u32_u24_e32 v5, 0x90, v5
	v_add3_u32 v13, v45, v5, v4
	ds_read_b128 v[4:7], v12
	ds_read_b128 v[8:11], v13 offset:36864
	s_waitcnt lgkmcnt(0)
	v_mfma_f32_16x16x32_bf16 v[4:7], v[4:7], v[8:11], 0
	ds_read_b128 v[8:11], v12 offset:64
	ds_read_b128 v[12:15], v13 offset:36928
	s_waitcnt lgkmcnt(0)
	v_mfma_f32_16x16x32_bf16 v[4:7], v[8:11], v[12:15], v[4:7]
	v_mov_b32_e32 v8, v185
	s_nop 0
	v_and_b32_e32 v9, 15, v8
	v_or_b32_e32 v10, v9, v16
	v_mul_lo_u32 v10, v10, s70
	v_and_b32_e32 v8, 48, v8
	v_add3_u32 v17, v45, v10, v8
	v_mul_u32_u24_e32 v9, 0x90, v9
	v_add3_u32 v18, v45, v9, v8
	ds_read_b128 v[8:11], v17 offset:18432
	ds_read_b128 v[12:15], v18 offset:55296
	s_waitcnt lgkmcnt(0)
	v_mfma_f32_16x16x32_bf16 v[4:7], v[8:11], v[12:15], v[4:7]
	ds_read_b128 v[8:11], v17 offset:18496
	ds_read_b128 v[12:15], v18 offset:55360
	s_waitcnt lgkmcnt(0)
	v_mfma_f32_16x16x32_bf16 v[4:7], v[8:11], v[12:15], v[4:7]
	v_mov_b32_e32 v8, v185
	s_nop 0
	v_and_b32_e32 v9, 15, v8
	v_or_b32_e32 v10, v9, v16
	v_mul_lo_u32 v10, v10, s70
	v_and_b32_e32 v8, 48, v8
	v_add3_u32 v17, v45, v10, v8
	v_mul_u32_u24_e32 v9, 0x90, v9
	v_add3_u32 v18, v45, v9, v8
	ds_read_b128 v[8:11], v17
	ds_read_b128 v[12:15], v18 offset:39168
	s_waitcnt lgkmcnt(0)
	v_mfma_f32_16x16x32_bf16 v[8:11], v[8:11], v[12:15], 0
	ds_read_b128 v[12:15], v17 offset:64
	ds_read_b128 v[18:21], v18 offset:39232
	s_waitcnt lgkmcnt(0)
	v_mfma_f32_16x16x32_bf16 v[8:11], v[12:15], v[18:21], v[8:11]
	v_mov_b32_e32 v12, v185
	s_nop 0
	v_and_b32_e32 v13, 15, v12
	v_or_b32_e32 v14, v13, v16
	v_mul_lo_u32 v14, v14, s70
	v_and_b32_e32 v12, 48, v12
	v_add3_u32 v17, v45, v14, v12
	v_mul_u32_u24_e32 v13, 0x90, v13
	v_add3_u32 v22, v45, v13, v12
	ds_read_b128 v[12:15], v17 offset:18432
	ds_read_b128 v[18:21], v22 offset:57600
	s_waitcnt lgkmcnt(0)
	v_mfma_f32_16x16x32_bf16 v[8:11], v[12:15], v[18:21], v[8:11]
	ds_read_b128 v[12:15], v17 offset:18496
	ds_read_b128 v[18:21], v22 offset:57664
	s_waitcnt lgkmcnt(0)
	v_mfma_f32_16x16x32_bf16 v[8:11], v[12:15], v[18:21], v[8:11]
	v_mov_b32_e32 v12, v185
	s_nop 0
	v_and_b32_e32 v13, 15, v12
	v_or_b32_e32 v14, v13, v16
	v_mul_lo_u32 v14, v14, s70
	v_and_b32_e32 v12, 48, v12
	v_add3_u32 v17, v45, v14, v12
	v_mul_u32_u24_e32 v13, 0x90, v13
	v_add3_u32 v22, v45, v13, v12
	ds_read_b128 v[12:15], v17
	ds_read_b128 v[18:21], v22 offset:41472
	s_waitcnt lgkmcnt(0)
	v_mfma_f32_16x16x32_bf16 v[12:15], v[12:15], v[18:21], 0
	ds_read_b128 v[18:21], v17 offset:64
	ds_read_b128 v[22:25], v22 offset:41536
	v_mov_b32_e32 v17, v185
	s_waitcnt lgkmcnt(0)
	v_mfma_f32_16x16x32_bf16 v[12:15], v[18:21], v[22:25], v[12:15]
	v_and_b32_e32 v18, 15, v17
	v_or_b32_e32 v19, v18, v16
	v_mul_lo_u32 v19, v19, s70
	v_and_b32_e32 v17, 48, v17
	v_add3_u32 v26, v45, v19, v17
	v_mul_u32_u24_e32 v18, 0x90, v18
	v_add3_u32 v17, v45, v18, v17
	ds_read_b128 v[18:21], v26 offset:18432
	ds_read_b128 v[22:25], v17 offset:59904
	s_waitcnt lgkmcnt(0)
	v_mfma_f32_16x16x32_bf16 v[12:15], v[18:21], v[22:25], v[12:15]
	ds_read_b128 v[18:21], v26 offset:18496
	ds_read_b128 v[22:25], v17 offset:59968
	v_mov_b32_e32 v17, v185
	s_waitcnt lgkmcnt(0)
	v_mfma_f32_16x16x32_bf16 v[12:15], v[18:21], v[22:25], v[12:15]
	v_and_b32_e32 v18, 15, v17
	v_or_b32_e32 v19, v18, v16
	v_mul_lo_u32 v19, v19, s70
	v_and_b32_e32 v17, 48, v17
	v_add3_u32 v26, v45, v19, v17
	v_mul_u32_u24_e32 v18, 0x90, v18
	v_add3_u32 v17, v45, v18, v17
	ds_read_b128 v[18:21], v26
	ds_read_b128 v[22:25], v17 offset:43776
	s_waitcnt lgkmcnt(0)
	v_mfma_f32_16x16x32_bf16 v[18:21], v[18:21], v[22:25], 0
	ds_read_b128 v[22:25], v26 offset:64
	ds_read_b128 v[26:29], v17 offset:43840
	v_mov_b32_e32 v17, v185
	s_waitcnt lgkmcnt(0)
	v_mfma_f32_16x16x32_bf16 v[18:21], v[22:25], v[26:29], v[18:21]
	v_and_b32_e32 v22, 15, v17
	v_or_b32_e32 v23, v22, v16
	v_mul_lo_u32 v23, v23, s70
	v_and_b32_e32 v17, 48, v17
	v_add3_u32 v30, v45, v23, v17
	v_mul_u32_u24_e32 v22, 0x90, v22
	v_add3_u32 v17, v45, v22, v17
	ds_read_b128 v[22:25], v30 offset:18432
	ds_read_b128 v[26:29], v17 offset:62208
	s_waitcnt lgkmcnt(0)
	v_mfma_f32_16x16x32_bf16 v[18:21], v[22:25], v[26:29], v[18:21]
	ds_read_b128 v[22:25], v30 offset:18496
	ds_read_b128 v[26:29], v17 offset:62272
	v_mov_b32_e32 v17, v185
	s_waitcnt lgkmcnt(0)
	v_mfma_f32_16x16x32_bf16 v[20:23], v[22:25], v[26:29], v[18:21]
	s_nop 2
	v_and_b32_e32 v18, 15, v17
	v_or_b32_e32 v19, v18, v16
	v_mul_lo_u32 v19, v19, s70
	v_and_b32_e32 v17, 48, v17
	v_add3_u32 v19, v45, v19, v17
	v_mul_u32_u24_e32 v18, 0x90, v18
	v_add3_u32 v17, v45, v18, v17
	ds_read_b128 v[24:27], v19
	ds_read_b128 v[28:31], v17 offset:46080
	s_waitcnt lgkmcnt(0)
	v_mfma_f32_16x16x32_bf16 v[24:27], v[24:27], v[28:31], 0
	ds_read_b128 v[28:31], v19 offset:64
	ds_read_b128 v[32:35], v17 offset:46144
	v_mov_b32_e32 v17, v185
	s_waitcnt lgkmcnt(0)
	v_mfma_f32_16x16x32_bf16 v[24:27], v[28:31], v[32:35], v[24:27]
	v_and_b32_e32 v18, 15, v17
	v_or_b32_e32 v19, v18, v16
	v_mul_lo_u32 v19, v19, s70
	v_and_b32_e32 v17, 48, v17
	v_add3_u32 v19, v45, v19, v17
	v_mul_u32_u24_e32 v18, 0x90, v18
	v_add3_u32 v17, v45, v18, v17
	ds_read_b128 v[28:31], v19 offset:18432
	ds_read_b128 v[32:35], v17 offset:64512
	s_waitcnt lgkmcnt(0)
	v_mfma_f32_16x16x32_bf16 v[24:27], v[28:31], v[32:35], v[24:27]
	ds_read_b128 v[28:31], v19 offset:18496
	ds_read_b128 v[32:35], v17 offset:64576
	v_mov_b32_e32 v17, v185
	s_waitcnt lgkmcnt(0)
; DI void gla3_item(const Params& p, int l, int gi, char* smem) {
;     ...
;   f32x4 o[8];
; #pragma unroll
;   for (int n = 0; n < 8; ++n) {
;     f32x4 a = lds_mm<2>(att, LP, wid * 16, vt, LP, n * 16, f32x4{0.f, 0.f, 0.f, 0.f});
;     o[n] = lds_mm<2>(qt, LP, wid * 16, st, LP, n * 16, a);
;   }
;   const float* gn = p.in[14] + (size_t)l * 128;
;   const u16* GR = (const u16*)(p.ws + O_GR);
;   u16* OG = (u16*)(p.ws + O_OG);
;   float gnv[8];
; #pragma unroll
;   for (int n = 0; n < 8; ++n) gnv[n] = gn[n * 16 + fr];
; #pragma unroll
;   for (int j = 0; j < 4; ++j) {
;     float ss = 0.f;
; #pragma unroll
;     for (int n = 0; n < 8; ++n) ss += o[n][j] * o[n][j];
;     ss += __shfl_xor(ss, 1); ss += __shfl_xor(ss, 2); ss += __shfl_xor(ss, 4); ss += __shfl_xor(ss, 8);
;     const float rs = rsqrtf(ss * (1.f / 128.f) + EPS);
;     const int t = wid * 16 + fq * 4 + j;
;     if (t < Lc) {
	v_mfma_f32_16x16x32_bf16 v[24:27], v[28:31], v[32:35], v[24:27]
	v_and_b32_e32 v18, 15, v17
	v_or_b32_e32 v19, v18, v16
	v_mul_lo_u32 v19, v19, s70
	v_and_b32_e32 v17, 48, v17
	v_add3_u32 v19, v45, v19, v17
	v_mul_u32_u24_e32 v18, 0x90, v18
	v_add3_u32 v17, v45, v18, v17
	ds_read_b128 v[28:31], v19
	ds_read_b128 v[32:35], v17 offset:48384
	s_waitcnt lgkmcnt(0)
	v_mfma_f32_16x16x32_bf16 v[28:31], v[28:31], v[32:35], 0
	ds_read_b128 v[32:35], v19 offset:64
	ds_read_b128 v[46:49], v17 offset:48448
	v_mov_b32_e32 v17, v185
	s_waitcnt lgkmcnt(0)
	v_mfma_f32_16x16x32_bf16 v[28:31], v[32:35], v[46:49], v[28:31]
	v_and_b32_e32 v18, 15, v17
	v_or_b32_e32 v19, v18, v16
	v_mul_lo_u32 v19, v19, s70
	v_and_b32_e32 v17, 48, v17
	v_add3_u32 v19, v45, v19, v17
	v_mad_u32_u24 v18, v18, s70, v45
	v_add3_u32 v17, v18, v17, s4
	ds_read_b128 v[32:35], v19 offset:18432
	ds_read_b128 v[46:49], v17 offset:11520
	s_waitcnt lgkmcnt(0)
	v_mfma_f32_16x16x32_bf16 v[28:31], v[32:35], v[46:49], v[28:31]
	ds_read_b128 v[32:35], v19 offset:18496
	ds_read_b128 v[46:49], v17 offset:11584
	v_mov_b32_e32 v17, v185
	s_waitcnt lgkmcnt(0)
	v_mfma_f32_16x16x32_bf16 v[28:31], v[32:35], v[46:49], v[28:31]
	v_and_b32_e32 v18, 15, v17
	v_or_b32_e32 v19, v18, v16
	v_mul_lo_u32 v19, v19, s70
	v_and_b32_e32 v17, 48, v17
	v_add3_u32 v19, v45, v19, v17
	v_mul_u32_u24_e32 v18, 0x90, v18
	v_add3_u32 v17, v45, v18, v17
	ds_read_b128 v[32:35], v19
	ds_read_b128 v[46:49], v17 offset:50688
	s_waitcnt lgkmcnt(0)
	v_mfma_f32_16x16x32_bf16 v[32:35], v[32:35], v[46:49], 0
	ds_read_b128 v[46:49], v19 offset:64
	ds_read_b128 v[50:53], v17 offset:50752
	v_mov_b32_e32 v17, v185
	s_waitcnt lgkmcnt(0)
	v_mfma_f32_16x16x32_bf16 v[32:35], v[46:49], v[50:53], v[32:35]
	v_and_b32_e32 v18, 15, v17
	v_or_b32_e32 v19, v18, v16
	v_mul_lo_u32 v19, v19, s70
	v_and_b32_e32 v17, 48, v17
	v_add3_u32 v19, v45, v19, v17
	v_mad_u32_u24 v18, v18, s70, v45
	v_add3_u32 v17, v18, v17, s4
	ds_read_b128 v[46:49], v19 offset:18432
	ds_read_b128 v[50:53], v17 offset:13824
	s_waitcnt lgkmcnt(0)
	v_mfma_f32_16x16x32_bf16 v[32:35], v[46:49], v[50:53], v[32:35]
	ds_read_b128 v[46:49], v19 offset:18496
	ds_read_b128 v[50:53], v17 offset:13888
	v_mov_b32_e32 v17, v185
	s_waitcnt lgkmcnt(0)
	v_mfma_f32_16x16x32_bf16 v[32:35], v[46:49], v[50:53], v[32:35]
	v_and_b32_e32 v18, 15, v17
	v_or_b32_e32 v19, v18, v16
	v_mul_lo_u32 v19, v19, s70
	v_and_b32_e32 v17, 48, v17
	v_add3_u32 v19, v45, v19, v17
	v_mul_u32_u24_e32 v18, 0x90, v18
	v_add3_u32 v17, v45, v18, v17
	ds_read_b128 v[46:49], v19
	ds_read_b128 v[50:53], v17 offset:52992
	s_waitcnt lgkmcnt(0)
	v_mfma_f32_16x16x32_bf16 v[46:49], v[46:49], v[50:53], 0
	ds_read_b128 v[50:53], v19 offset:64
	ds_read_b128 v[56:59], v17 offset:53056
	v_mov_b32_e32 v17, v185
	s_waitcnt lgkmcnt(0)
	v_mfma_f32_16x16x32_bf16 v[46:49], v[50:53], v[56:59], v[46:49]
	v_and_b32_e32 v18, 15, v17
	v_or_b32_e32 v16, v18, v16
	v_mul_lo_u32 v16, v16, s70
	v_and_b32_e32 v17, 48, v17
	v_add3_u32 v38, v45, v16, v17
	v_mad_u32_u24 v16, v18, s70, v45
	v_add3_u32 v39, v16, v17, s4
	ds_read_b128 v[16:19], v38 offset:18432
	ds_read_b128 v[50:53], v39 offset:16128
	s_waitcnt lgkmcnt(0)
	v_mfma_f32_16x16x32_bf16 v[16:19], v[16:19], v[50:53], v[46:49]
	s_nop 2
	ds_read_b128 v[46:49], v38 offset:18496
	ds_read_b128 v[50:53], v39 offset:16192
	s_waitcnt lgkmcnt(0)
	v_mfma_f32_16x16x32_bf16 v[16:19], v[46:49], v[50:53], v[16:19]
	global_load_dword v49, v36, s[46:47]
	global_load_dword v48, v36, s[46:47] offset:64
	global_load_dword v47, v36, s[46:47] offset:128
	global_load_dword v46, v36, s[46:47] offset:192
	global_load_dword v45, v36, s[46:47] offset:256
	global_load_dword v43, v36, s[46:47] offset:320
	global_load_dword v42, v36, s[46:47] offset:384
	global_load_dword v41, v36, s[46:47] offset:448
	v_cndmask_b32_e32 v36, v190, v192, vcc
	v_cmp_lt_i32_e32 vcc, v193, v191
	v_lshlrev_b32_e32 v50, 2, v36
	s_nop 0
	v_cndmask_b32_e32 v36, v190, v193, vcc
	v_cmp_lt_i32_e32 vcc, v194, v191
	v_lshlrev_b32_e32 v51, 2, v36
	s_nop 0
	v_cndmask_b32_e32 v36, v190, v194, vcc
	v_cmp_lt_i32_e32 vcc, v195, v191
	v_lshlrev_b32_e32 v52, 2, v36
	s_nop 0
	v_cndmask_b32_e32 v36, v190, v195, vcc
	v_lshlrev_b32_e32 v53, 2, v36
	v_mul_f32_e32 v36, v8, v8
	v_fmac_f32_e32 v36, v4, v4
	v_fmac_f32_e32 v36, v12, v12
	v_fmac_f32_e32 v36, v20, v20
	v_fmac_f32_e32 v36, v24, v24
	v_fmac_f32_e32 v36, v28, v28
	v_fmac_f32_e32 v36, v32, v32
	v_fmac_f32_e32 v36, v16, v16
	ds_bpermute_b32 v38, v50, v36
	v_cmp_lt_i32_e32 vcc, v37, v2
	s_waitcnt lgkmcnt(0)
	v_add_f32_e32 v36, v36, v38
	ds_bpermute_b32 v38, v51, v36
	s_waitcnt lgkmcnt(0)
	v_add_f32_e32 v36, v36, v38
	ds_bpermute_b32 v38, v52, v36
	s_waitcnt lgkmcnt(0)
	v_add_f32_e32 v36, v36, v38
	ds_bpermute_b32 v38, v53, v36
	s_and_saveexec_b64 s[4:5], vcc
	s_cbranch_execz .LBB0_1900
; DI float bf2f(u16 h) { return __uint_as_float(((unsigned)h) << 16); }
; DI float sigmoidf_(float x) { return __builtin_amdgcn_rcpf(1.f + __expf(-x)); }
; DI void gla3_item(const Params& p, int l, int gi, char* smem) {
;     ...
;   for (int j = 0; j < 4; ++j) {
;     float ss = 0.f;
; #pragma unroll
;     for (int n = 0; n < 8; ++n) ss += o[n][j] * o[n][j];
;     ss += __shfl_xor(ss, 1); ss += __shfl_xor(ss, 2); ss += __shfl_xor(ss, 4); ss += __shfl_xor(ss, 8);
;     const float rs = rsqrtf(ss * (1.f / 128.f) + EPS);
;     const int t = wid * 16 + fq * 4 + j;
;     if (t < Lc) {
;       const size_t ro = (size_t)(row0 + t) * 512 + h * 128;
;       u16 grv[8];
; #pragma unroll
;       for (int n = 0; n < 8; ++n) grv[n] = GR[ro + n * 16 + fr];
; #pragma unroll
;       for (int n = 0; n < 8; ++n) {
;         const float gr = bf2f(grv[n]);
;         OG[ro + n * 16 + fr] = f2bf(o[n][j] * rs * gnv[n] * gr * sigmoidf_(gr));
;       }
;     }
	s_waitcnt lgkmcnt(0)
	v_add_f32_e32 v36, v36, v38
	v_fmamk_f32 v36, v36, 0x3c000000, v186
	v_cmp_gt_f32_e32 vcc, s1, v36
	v_mul_f32_e32 v38, 0x4b800000, v36
	v_readlane_b32 s6, v252, 35
	v_cndmask_b32_e32 v36, v36, v38, vcc
	v_rsq_f32_e32 v36, v36
	v_readlane_b32 s7, v252, 36
	v_mul_f32_e32 v38, 0x45800000, v36
	v_cndmask_b32_e32 v56, v36, v38, vcc
	v_add_u32_e32 v36, v37, v44
	v_ashrrev_i32_e32 v37, 31, v36
	v_lshlrev_b64 v[36:37], 10, v[36:37]
	v_lshl_or_b32 v36, v1, 1, v36
	v_lshl_add_u64 v[38:39], s[6:7], 0, v[36:37]
	v_lshl_add_u64 v[38:39], v[38:39], 0, v[172:173]
	global_load_ushort v160, v[38:39], off
	global_load_ushort v161, v[38:39], off offset:32
	global_load_ushort v162, v[38:39], off offset:64
	global_load_ushort v163, v[38:39], off offset:96
	global_load_ushort v164, v[38:39], off offset:128
	global_load_ushort v165, v[38:39], off offset:160
	global_load_ushort v166, v[38:39], off offset:192
	global_load_ushort v167, v[38:39], off offset:224
	v_mul_f32_e32 v4, v4, v56
	s_waitcnt vmcnt(15)
	v_mul_f32_e32 v4, v49, v4
	v_readlane_b32 s6, v253, 11
	v_readlane_b32 s7, v253, 12
	v_mul_f32_e32 v8, v8, v56
	s_waitcnt vmcnt(14)
	v_mul_f32_e32 v8, v48, v8
	v_lshl_add_u64 v[36:37], s[6:7], 0, v[36:37]
	v_lshl_add_u64 v[36:37], v[36:37], 0, v[172:173]
	s_waitcnt vmcnt(7)
	v_lshlrev_b32_e32 v57, 16, v160
	v_mul_f32_e32 v4, v4, v57
	v_mul_f32_e32 v57, 0xbfb8aa3b, v57
	v_exp_f32_e32 v57, v57
	s_nop 0
	v_add_f32_e32 v57, 1.0, v57
	v_rcp_f32_e32 v57, v57
	s_nop 0
	v_mul_f32_e32 v4, v4, v57
	v_cvt_pk_bf16_f32 v4, v4, s0
	global_store_short v[36:37], v4, off
	s_waitcnt vmcnt(7)
	v_lshlrev_b32_e32 v4, 16, v161
	v_mul_f32_e32 v8, v8, v4
	v_mul_f32_e32 v4, 0xbfb8aa3b, v4
	v_exp_f32_e32 v4, v4
	s_nop 0
	v_add_f32_e32 v4, 1.0, v4
	v_rcp_f32_e32 v4, v4
	s_nop 0
	v_mul_f32_e32 v4, v8, v4
	v_cvt_pk_bf16_f32 v4, v4, s0
	global_store_short v[36:37], v4, off offset:32
	v_mul_f32_e32 v8, v12, v56
	v_mul_f32_e32 v8, v47, v8
	s_waitcnt vmcnt(7)
	v_lshlrev_b32_e32 v4, 16, v162
	v_mul_f32_e32 v8, v8, v4
	v_mul_f32_e32 v4, 0xbfb8aa3b, v4
	v_exp_f32_e32 v4, v4
	s_nop 0
	v_add_f32_e32 v4, 1.0, v4
	v_rcp_f32_e32 v4, v4
	s_nop 0
	v_mul_f32_e32 v4, v8, v4
	v_cvt_pk_bf16_f32 v4, v4, s0
	global_store_short v[36:37], v4, off offset:64
	v_mul_f32_e32 v8, v20, v56
	v_mul_f32_e32 v8, v46, v8
	s_waitcnt vmcnt(7)
	v_lshlrev_b32_e32 v4, 16, v163
	v_mul_f32_e32 v8, v8, v4
	v_mul_f32_e32 v4, 0xbfb8aa3b, v4
	v_exp_f32_e32 v4, v4
	s_nop 0
	v_add_f32_e32 v4, 1.0, v4
	v_rcp_f32_e32 v4, v4
	s_nop 0
	v_mul_f32_e32 v4, v8, v4
	v_cvt_pk_bf16_f32 v4, v4, s0
	global_store_short v[36:37], v4, off offset:96
	v_mul_f32_e32 v8, v24, v56
	v_mul_f32_e32 v8, v45, v8
	s_waitcnt vmcnt(7)
	v_lshlrev_b32_e32 v4, 16, v164
	v_mul_f32_e32 v8, v8, v4
	v_mul_f32_e32 v4, 0xbfb8aa3b, v4
	v_exp_f32_e32 v4, v4
	s_nop 0
	v_add_f32_e32 v4, 1.0, v4
	v_rcp_f32_e32 v4, v4
	s_nop 0
	v_mul_f32_e32 v4, v8, v4
	v_cvt_pk_bf16_f32 v4, v4, s0
	global_store_short v[36:37], v4, off offset:128
	v_mul_f32_e32 v8, v28, v56
	v_mul_f32_e32 v8, v43, v8
	s_waitcnt vmcnt(7)
	v_lshlrev_b32_e32 v4, 16, v165
	v_mul_f32_e32 v8, v8, v4
	v_mul_f32_e32 v4, 0xbfb8aa3b, v4
	v_exp_f32_e32 v4, v4
	s_nop 0
	v_add_f32_e32 v4, 1.0, v4
	v_rcp_f32_e32 v4, v4
	s_nop 0
	v_mul_f32_e32 v4, v8, v4
	v_cvt_pk_bf16_f32 v4, v4, s0
	global_store_short v[36:37], v4, off offset:160
	v_mul_f32_e32 v8, v32, v56
	v_mul_f32_e32 v8, v42, v8
	s_waitcnt vmcnt(7)
	v_lshlrev_b32_e32 v4, 16, v166
	v_mul_f32_e32 v8, v8, v4
	v_mul_f32_e32 v4, 0xbfb8aa3b, v4
	v_exp_f32_e32 v4, v4
	s_nop 0
	v_add_f32_e32 v4, 1.0, v4
	v_rcp_f32_e32 v4, v4
	s_nop 0
	v_mul_f32_e32 v4, v8, v4
	v_cvt_pk_bf16_f32 v4, v4, s0
	global_store_short v[36:37], v4, off offset:192
	v_mul_f32_e32 v8, v16, v56
	v_mul_f32_e32 v8, v41, v8
	s_waitcnt vmcnt(7)
	v_lshlrev_b32_e32 v4, 16, v167
	v_mul_f32_e32 v8, v8, v4
	v_mul_f32_e32 v4, 0xbfb8aa3b, v4
	v_exp_f32_e32 v4, v4
	s_nop 0
	v_add_f32_e32 v4, 1.0, v4
	v_rcp_f32_e32 v4, v4
	s_nop 0
	v_mul_f32_e32 v4, v8, v4
	v_cvt_pk_bf16_f32 v4, v4, s0
	global_store_short v[36:37], v4, off offset:224
.LBB0_1900:
	s_or_b64 exec, exec, s[4:5]
	v_mul_f32_e32 v4, v9, v9
	v_fmac_f32_e32 v4, v5, v5
	v_fmac_f32_e32 v4, v13, v13
	v_fmac_f32_e32 v4, v21, v21
	v_fmac_f32_e32 v4, v25, v25
	v_fmac_f32_e32 v4, v29, v29
	v_fmac_f32_e32 v4, v33, v33
	v_fmac_f32_e32 v4, v17, v17
	ds_bpermute_b32 v8, v50, v4
	v_cmp_lt_i32_e32 vcc, v55, v2
	s_waitcnt lgkmcnt(0)
	v_add_f32_e32 v4, v4, v8
	ds_bpermute_b32 v8, v51, v4
	s_waitcnt lgkmcnt(0)
	v_add_f32_e32 v4, v4, v8
	ds_bpermute_b32 v8, v52, v4
	s_waitcnt lgkmcnt(0)
	v_add_f32_e32 v4, v4, v8
	ds_bpermute_b32 v8, v53, v4
	s_and_saveexec_b64 s[4:5], vcc
	s_cbranch_execz .LBB0_1902
; DI float bf2f(u16 h) { return __uint_as_float(((unsigned)h) << 16); }
; DI float sigmoidf_(float x) { return __builtin_amdgcn_rcpf(1.f + __expf(-x)); }
; DI void gla3_item(const Params& p, int l, int gi, char* smem) {
;     ...
;   for (int j = 0; j < 4; ++j) {
;     float ss = 0.f;
; #pragma unroll
;     for (int n = 0; n < 8; ++n) ss += o[n][j] * o[n][j];
;     ss += __shfl_xor(ss, 1); ss += __shfl_xor(ss, 2); ss += __shfl_xor(ss, 4); ss += __shfl_xor(ss, 8);
;     const float rs = rsqrtf(ss * (1.f / 128.f) + EPS);
;     const int t = wid * 16 + fq * 4 + j;
;     if (t < Lc) {
;       const size_t ro = (size_t)(row0 + t) * 512 + h * 128;
;       u16 grv[8];
; #pragma unroll
;       for (int n = 0; n < 8; ++n) grv[n] = GR[ro + n * 16 + fr];
; #pragma unroll
;       for (int n = 0; n < 8; ++n) {
;         const float gr = bf2f(grv[n]);
;         OG[ro + n * 16 + fr] = f2bf(o[n][j] * rs * gnv[n] * gr * sigmoidf_(gr));
;       }
;     }
	s_waitcnt lgkmcnt(0)
	v_add_f32_e32 v4, v4, v8
	v_fmamk_f32 v4, v4, 0x3c000000, v186
	v_cmp_gt_f32_e32 vcc, s1, v4
	v_mul_f32_e32 v8, 0x4b800000, v4
	v_add_u32_e32 v36, v55, v44
	v_cndmask_b32_e32 v4, v4, v8, vcc
	v_rsq_f32_e32 v4, v4
	v_ashrrev_i32_e32 v37, 31, v36
	v_lshlrev_b64 v[38:39], 10, v[36:37]
	v_readlane_b32 s6, v252, 35
	v_lshl_or_b32 v38, v1, 1, v38
	v_readlane_b32 s7, v252, 36
	v_mul_f32_e32 v8, 0x45800000, v4
	v_cndmask_b32_e32 v8, v4, v8, vcc
	v_lshl_add_u64 v[36:37], s[6:7], 0, v[38:39]
	v_lshl_add_u64 v[36:37], v[36:37], 0, v[172:173]
	global_load_ushort v160, v[36:37], off
	global_load_ushort v161, v[36:37], off offset:32
	global_load_ushort v162, v[36:37], off offset:64
	global_load_ushort v163, v[36:37], off offset:96
	global_load_ushort v164, v[36:37], off offset:128
	global_load_ushort v165, v[36:37], off offset:160
	global_load_ushort v166, v[36:37], off offset:192
	global_load_ushort v167, v[36:37], off offset:224
	v_mul_f32_e32 v5, v5, v8
	s_waitcnt vmcnt(15)
	v_mul_f32_e32 v5, v49, v5
	v_readlane_b32 s6, v253, 11
	v_readlane_b32 s7, v253, 12
	v_mul_f32_e32 v9, v9, v8
	s_waitcnt vmcnt(14)
	v_mul_f32_e32 v9, v48, v9
	v_lshl_add_u64 v[38:39], s[6:7], 0, v[38:39]
	s_waitcnt vmcnt(7)
	v_lshlrev_b32_e32 v4, 16, v160
	v_mul_f32_e32 v5, v5, v4
	v_mul_f32_e32 v4, 0xbfb8aa3b, v4
	v_exp_f32_e32 v4, v4
	s_nop 0
	v_add_f32_e32 v4, 1.0, v4
	v_rcp_f32_e32 v4, v4
	s_nop 0
	v_mul_f32_e32 v4, v5, v4
	v_cvt_pk_bf16_f32 v12, v4, s0
	v_lshl_add_u64 v[4:5], v[38:39], 0, v[172:173]
	global_store_short v[4:5], v12, off
	s_waitcnt vmcnt(7)
	v_lshlrev_b32_e32 v12, 16, v161
	v_mul_f32_e32 v9, v9, v12
	v_mul_f32_e32 v12, 0xbfb8aa3b, v12
	v_exp_f32_e32 v12, v12
	s_nop 0
	v_add_f32_e32 v12, 1.0, v12
	v_rcp_f32_e32 v12, v12
	s_nop 0
	v_mul_f32_e32 v9, v9, v12
	v_cvt_pk_bf16_f32 v9, v9, s0
	global_store_short v[4:5], v9, off offset:32
	v_mul_f32_e32 v12, v13, v8
	v_mul_f32_e32 v12, v47, v12
	s_waitcnt vmcnt(7)
	v_lshlrev_b32_e32 v9, 16, v162
	v_mul_f32_e32 v12, v12, v9
	v_mul_f32_e32 v9, 0xbfb8aa3b, v9
	v_exp_f32_e32 v9, v9
	s_nop 0
	v_add_f32_e32 v9, 1.0, v9
	v_rcp_f32_e32 v9, v9
	s_nop 0
	v_mul_f32_e32 v9, v12, v9
	v_cvt_pk_bf16_f32 v9, v9, s0
	global_store_short v[4:5], v9, off offset:64
	v_mul_f32_e32 v12, v21, v8
	v_mul_f32_e32 v12, v46, v12
	s_waitcnt vmcnt(7)
	v_lshlrev_b32_e32 v9, 16, v163
	v_mul_f32_e32 v12, v12, v9
	v_mul_f32_e32 v9, 0xbfb8aa3b, v9
	v_exp_f32_e32 v9, v9
	s_nop 0
	v_add_f32_e32 v9, 1.0, v9
	v_rcp_f32_e32 v9, v9
	s_nop 0
	v_mul_f32_e32 v9, v12, v9
	v_cvt_pk_bf16_f32 v9, v9, s0
	global_store_short v[4:5], v9, off offset:96
	v_mul_f32_e32 v12, v25, v8
	v_mul_f32_e32 v12, v45, v12
	s_waitcnt vmcnt(7)
	v_lshlrev_b32_e32 v9, 16, v164
	v_mul_f32_e32 v12, v12, v9
	v_mul_f32_e32 v9, 0xbfb8aa3b, v9
	v_exp_f32_e32 v9, v9
	s_nop 0
	v_add_f32_e32 v9, 1.0, v9
	v_rcp_f32_e32 v9, v9
	s_nop 0
	v_mul_f32_e32 v9, v12, v9
	v_cvt_pk_bf16_f32 v9, v9, s0
	global_store_short v[4:5], v9, off offset:128
	v_mul_f32_e32 v12, v29, v8
	v_mul_f32_e32 v12, v43, v12
	s_waitcnt vmcnt(7)
	v_lshlrev_b32_e32 v9, 16, v165
	v_mul_f32_e32 v12, v12, v9
	v_mul_f32_e32 v9, 0xbfb8aa3b, v9
	v_exp_f32_e32 v9, v9
	s_nop 0
	v_add_f32_e32 v9, 1.0, v9
	v_rcp_f32_e32 v9, v9
	s_nop 0
	v_mul_f32_e32 v9, v12, v9
	v_cvt_pk_bf16_f32 v9, v9, s0
	global_store_short v[4:5], v9, off offset:160
	v_mul_f32_e32 v12, v33, v8
	v_mul_f32_e32 v12, v42, v12
	v_mul_f32_e32 v8, v17, v8
	v_mul_f32_e32 v8, v41, v8
	s_waitcnt vmcnt(7)
	v_lshlrev_b32_e32 v9, 16, v166
	v_mul_f32_e32 v12, v12, v9
	v_mul_f32_e32 v9, 0xbfb8aa3b, v9
	v_exp_f32_e32 v9, v9
	s_nop 0
	v_add_f32_e32 v9, 1.0, v9
	v_rcp_f32_e32 v9, v9
	s_nop 0
	v_mul_f32_e32 v9, v12, v9
	v_cvt_pk_bf16_f32 v9, v9, s0
	global_store_short v[4:5], v9, off offset:192
	s_waitcnt vmcnt(7)
	v_lshlrev_b32_e32 v9, 16, v167
	v_mul_f32_e32 v8, v8, v9
	v_mul_f32_e32 v9, 0xbfb8aa3b, v9
	v_exp_f32_e32 v9, v9
	s_nop 0
	v_add_f32_e32 v9, 1.0, v9
	v_rcp_f32_e32 v9, v9
	s_nop 0
	v_mul_f32_e32 v8, v8, v9
	v_cvt_pk_bf16_f32 v8, v8, s0
	global_store_short v[4:5], v8, off offset:224
.LBB0_1902:
	s_or_b64 exec, exec, s[4:5]
	v_mul_f32_e32 v4, v10, v10
	v_fmac_f32_e32 v4, v6, v6
	v_fmac_f32_e32 v4, v14, v14
	v_fmac_f32_e32 v4, v22, v22
	v_fmac_f32_e32 v4, v26, v26
	v_fmac_f32_e32 v4, v30, v30
	v_fmac_f32_e32 v4, v34, v34
	v_fmac_f32_e32 v4, v18, v18
	ds_bpermute_b32 v5, v50, v4
	v_cmp_lt_i32_e32 vcc, v54, v2
	s_waitcnt lgkmcnt(0)
	v_add_f32_e32 v4, v4, v5
	ds_bpermute_b32 v5, v51, v4
	s_waitcnt lgkmcnt(0)
	v_add_f32_e32 v4, v4, v5
	ds_bpermute_b32 v5, v52, v4
	s_waitcnt lgkmcnt(0)
	v_add_f32_e32 v4, v4, v5
	ds_bpermute_b32 v5, v53, v4
	s_and_saveexec_b64 s[4:5], vcc
	s_cbranch_execz .LBB0_1904
; DI float bf2f(u16 h) { return __uint_as_float(((unsigned)h) << 16); }
; DI float sigmoidf_(float x) { return __builtin_amdgcn_rcpf(1.f + __expf(-x)); }
; DI void gla3_item(const Params& p, int l, int gi, char* smem) {
;     ...
;   for (int j = 0; j < 4; ++j) {
;     float ss = 0.f;
; #pragma unroll
;     for (int n = 0; n < 8; ++n) ss += o[n][j] * o[n][j];
;     ss += __shfl_xor(ss, 1); ss += __shfl_xor(ss, 2); ss += __shfl_xor(ss, 4); ss += __shfl_xor(ss, 8);
;     const float rs = rsqrtf(ss * (1.f / 128.f) + EPS);
;     const int t = wid * 16 + fq * 4 + j;
;     if (t < Lc) {
;       const size_t ro = (size_t)(row0 + t) * 512 + h * 128;
;       u16 grv[8];
; #pragma unroll
;       for (int n = 0; n < 8; ++n) grv[n] = GR[ro + n * 16 + fr];
; #pragma unroll
;       for (int n = 0; n < 8; ++n) {
;         const float gr = bf2f(grv[n]);
;         OG[ro + n * 16 + fr] = f2bf(o[n][j] * rs * gnv[n] * gr * sigmoidf_(gr));
;       }
;     }
	s_waitcnt lgkmcnt(0)
	v_add_f32_e32 v4, v4, v5
	v_fmamk_f32 v4, v4, 0x3c000000, v186
	v_cmp_gt_f32_e32 vcc, s1, v4
	v_mul_f32_e32 v5, 0x4b800000, v4
	v_readlane_b32 s6, v252, 35
	v_cndmask_b32_e32 v4, v4, v5, vcc
	v_rsq_f32_e32 v4, v4
	v_readlane_b32 s7, v252, 36
	v_mul_f32_e32 v5, 0x45800000, v4
	v_cndmask_b32_e32 v12, v4, v5, vcc
	v_add_u32_e32 v4, v54, v44
	v_ashrrev_i32_e32 v5, 31, v4
	v_lshlrev_b64 v[4:5], 10, v[4:5]
	v_lshl_or_b32 v4, v1, 1, v4
	v_lshl_add_u64 v[8:9], s[6:7], 0, v[4:5]
	v_lshl_add_u64 v[8:9], v[8:9], 0, v[172:173]
	global_load_ushort v160, v[8:9], off
	global_load_ushort v161, v[8:9], off offset:32
	global_load_ushort v162, v[8:9], off offset:64
	global_load_ushort v163, v[8:9], off offset:96
	global_load_ushort v164, v[8:9], off offset:128
	global_load_ushort v165, v[8:9], off offset:160
	global_load_ushort v166, v[8:9], off offset:192
	global_load_ushort v167, v[8:9], off offset:224
	v_mul_f32_e32 v6, v6, v12
	s_waitcnt vmcnt(15)
	v_mul_f32_e32 v6, v49, v6
	v_readlane_b32 s6, v253, 11
	v_readlane_b32 s7, v253, 12
	v_mul_f32_e32 v10, v10, v12
	s_waitcnt vmcnt(14)
	v_mul_f32_e32 v10, v48, v10
	v_lshl_add_u64 v[4:5], s[6:7], 0, v[4:5]
	v_lshl_add_u64 v[4:5], v[4:5], 0, v[172:173]
	s_waitcnt vmcnt(7)
	v_lshlrev_b32_e32 v13, 16, v160
	v_mul_f32_e32 v6, v6, v13
	v_mul_f32_e32 v13, 0xbfb8aa3b, v13
	v_exp_f32_e32 v13, v13
	s_nop 0
	v_add_f32_e32 v13, 1.0, v13
	v_rcp_f32_e32 v13, v13
	s_nop 0
	v_mul_f32_e32 v6, v6, v13
	v_cvt_pk_bf16_f32 v6, v6, s0
	global_store_short v[4:5], v6, off
	s_waitcnt vmcnt(7)
	v_lshlrev_b32_e32 v6, 16, v161
	v_mul_f32_e32 v10, v10, v6
	v_mul_f32_e32 v6, 0xbfb8aa3b, v6
	v_exp_f32_e32 v6, v6
	s_nop 0
	v_add_f32_e32 v6, 1.0, v6
	v_rcp_f32_e32 v6, v6
	s_nop 0
	v_mul_f32_e32 v6, v10, v6
	v_cvt_pk_bf16_f32 v6, v6, s0
	global_store_short v[4:5], v6, off offset:32
	v_mul_f32_e32 v10, v14, v12
	v_mul_f32_e32 v10, v47, v10
	s_waitcnt vmcnt(7)
	v_lshlrev_b32_e32 v6, 16, v162
	v_mul_f32_e32 v10, v10, v6
	v_mul_f32_e32 v6, 0xbfb8aa3b, v6
	v_exp_f32_e32 v6, v6
	s_nop 0
	v_add_f32_e32 v6, 1.0, v6
	v_rcp_f32_e32 v6, v6
	s_nop 0
	v_mul_f32_e32 v6, v10, v6
	v_cvt_pk_bf16_f32 v6, v6, s0
	global_store_short v[4:5], v6, off offset:64
	v_mul_f32_e32 v10, v22, v12
	v_mul_f32_e32 v10, v46, v10
	s_waitcnt vmcnt(7)
	v_lshlrev_b32_e32 v6, 16, v163
	v_mul_f32_e32 v10, v10, v6
	v_mul_f32_e32 v6, 0xbfb8aa3b, v6
	v_exp_f32_e32 v6, v6
	s_nop 0
	v_add_f32_e32 v6, 1.0, v6
	v_rcp_f32_e32 v6, v6
	s_nop 0
	v_mul_f32_e32 v6, v10, v6
	v_cvt_pk_bf16_f32 v6, v6, s0
	global_store_short v[4:5], v6, off offset:96
	v_mul_f32_e32 v10, v26, v12
	v_mul_f32_e32 v10, v45, v10
	s_waitcnt vmcnt(7)
	v_lshlrev_b32_e32 v6, 16, v164
	v_mul_f32_e32 v10, v10, v6
	v_mul_f32_e32 v6, 0xbfb8aa3b, v6
	v_exp_f32_e32 v6, v6
	s_nop 0
	v_add_f32_e32 v6, 1.0, v6
	v_rcp_f32_e32 v6, v6
	s_nop 0
	v_mul_f32_e32 v6, v10, v6
	v_cvt_pk_bf16_f32 v6, v6, s0
	global_store_short v[4:5], v6, off offset:128
	v_mul_f32_e32 v10, v30, v12
	v_mul_f32_e32 v10, v43, v10
	s_waitcnt vmcnt(7)
	v_lshlrev_b32_e32 v6, 16, v165
	v_mul_f32_e32 v10, v10, v6
	v_mul_f32_e32 v6, 0xbfb8aa3b, v6
	v_exp_f32_e32 v6, v6
	s_nop 0
	v_add_f32_e32 v6, 1.0, v6
	v_rcp_f32_e32 v6, v6
	s_nop 0
	v_mul_f32_e32 v6, v10, v6
	v_cvt_pk_bf16_f32 v6, v6, s0
	global_store_short v[4:5], v6, off offset:160
	v_mul_f32_e32 v10, v34, v12
	v_mul_f32_e32 v10, v42, v10
	s_waitcnt vmcnt(7)
	v_lshlrev_b32_e32 v6, 16, v166
	v_mul_f32_e32 v10, v10, v6
	v_mul_f32_e32 v6, 0xbfb8aa3b, v6
	v_exp_f32_e32 v6, v6
	s_nop 0
	v_add_f32_e32 v6, 1.0, v6
	v_rcp_f32_e32 v6, v6
	s_nop 0
	v_mul_f32_e32 v6, v10, v6
	v_cvt_pk_bf16_f32 v6, v6, s0
	global_store_short v[4:5], v6, off offset:192
	v_mul_f32_e32 v8, v18, v12
	v_mul_f32_e32 v8, v41, v8
	s_waitcnt vmcnt(7)
	v_lshlrev_b32_e32 v6, 16, v167
	v_mul_f32_e32 v8, v8, v6
	v_mul_f32_e32 v6, 0xbfb8aa3b, v6
	v_exp_f32_e32 v6, v6
	s_nop 0
	v_add_f32_e32 v6, 1.0, v6
	v_rcp_f32_e32 v6, v6
	s_nop 0
	v_mul_f32_e32 v6, v8, v6
	v_cvt_pk_bf16_f32 v6, v6, s0
	global_store_short v[4:5], v6, off offset:224
; DI float bf2f(u16 h) { return __uint_as_float(((unsigned)h) << 16); }
; DI float sigmoidf_(float x) { return __builtin_amdgcn_rcpf(1.f + __expf(-x)); }
; DI void gla3_item(const Params& p, int l, int gi, char* smem) {
;     ...
;   for (int j = 0; j < 4; ++j) {
;     float ss = 0.f;
; #pragma unroll
;     for (int n = 0; n < 8; ++n) ss += o[n][j] * o[n][j];
;     ss += __shfl_xor(ss, 1); ss += __shfl_xor(ss, 2); ss += __shfl_xor(ss, 4); ss += __shfl_xor(ss, 8);
;     const float rs = rsqrtf(ss * (1.f / 128.f) + EPS);
;     const int t = wid * 16 + fq * 4 + j;
;     if (t < Lc) {
;       const size_t ro = (size_t)(row0 + t) * 512 + h * 128;
;       u16 grv[8];
; #pragma unroll
;       for (int n = 0; n < 8; ++n) grv[n] = GR[ro + n * 16 + fr];
; #pragma unroll
;       for (int n = 0; n < 8; ++n) {
;         const float gr = bf2f(grv[n]);
;         OG[ro + n * 16 + fr] = f2bf(o[n][j] * rs * gnv[n] * gr * sigmoidf_(gr));
;       }
;     }
.LBB0_1904:
	s_or_b64 exec, exec, s[4:5]
	v_mul_f32_e32 v4, v11, v11
	v_fmac_f32_e32 v4, v7, v7
	v_fmac_f32_e32 v4, v15, v15
	v_fmac_f32_e32 v4, v23, v23
	v_fmac_f32_e32 v4, v27, v27
	v_fmac_f32_e32 v4, v31, v31
	v_fmac_f32_e32 v4, v35, v35
	v_fmac_f32_e32 v4, v19, v19
	s_waitcnt lgkmcnt(0)
	ds_bpermute_b32 v5, v50, v4
	v_cmp_lt_i32_e32 vcc, v40, v2
	s_waitcnt lgkmcnt(0)
	v_add_f32_e32 v4, v4, v5
	ds_bpermute_b32 v5, v51, v4
	s_waitcnt lgkmcnt(0)
	v_add_f32_e32 v4, v4, v5
	ds_bpermute_b32 v5, v52, v4
	s_waitcnt lgkmcnt(0)
	v_add_f32_e32 v4, v4, v5
	ds_bpermute_b32 v5, v53, v4
	s_and_saveexec_b64 s[4:5], vcc
	s_cbranch_execz .LBB0_1841
	s_waitcnt lgkmcnt(0)
	v_add_f32_e32 v2, v4, v5
	v_fmamk_f32 v2, v2, 0x3c000000, v186
	v_cmp_gt_f32_e32 vcc, s1, v2
	v_mul_f32_e32 v4, 0x4b800000, v2
	v_readlane_b32 s6, v252, 35
	v_cndmask_b32_e32 v2, v2, v4, vcc
	v_rsq_f32_e32 v2, v2
	v_readlane_b32 s7, v252, 36
	v_mul_f32_e32 v4, 0x45800000, v2
	v_cndmask_b32_e32 v2, v2, v4, vcc
	v_add_u32_e32 v4, v40, v44
	v_ashrrev_i32_e32 v5, 31, v4
	v_lshlrev_b64 v[4:5], 10, v[4:5]
	v_lshl_or_b32 v4, v1, 1, v4
	v_lshl_add_u64 v[8:9], s[6:7], 0, v[4:5]
	v_lshl_add_u64 v[8:9], v[8:9], 0, v[172:173]
	global_load_ushort v160, v[8:9], off
	global_load_ushort v161, v[8:9], off offset:32
	global_load_ushort v162, v[8:9], off offset:64
	global_load_ushort v163, v[8:9], off offset:96
	global_load_ushort v164, v[8:9], off offset:128
	global_load_ushort v165, v[8:9], off offset:160
	global_load_ushort v166, v[8:9], off offset:192
	global_load_ushort v167, v[8:9], off offset:224
	v_mul_f32_e32 v6, v7, v2
	s_waitcnt vmcnt(15)
	v_mul_f32_e32 v6, v49, v6
	v_readlane_b32 s6, v253, 11
	v_readlane_b32 s7, v253, 12
	s_waitcnt vmcnt(7)
	v_lshlrev_b32_e32 v1, 16, v160
	v_mul_f32_e32 v6, v6, v1
	v_mul_f32_e32 v1, 0xbfb8aa3b, v1
	v_exp_f32_e32 v1, v1
	v_lshl_add_u64 v[4:5], s[6:7], 0, v[4:5]
	v_lshl_add_u64 v[4:5], v[4:5], 0, v[172:173]
	v_add_f32_e32 v1, 1.0, v1
	v_rcp_f32_e32 v1, v1
	s_nop 0
	v_mul_f32_e32 v1, v6, v1
	v_cvt_pk_bf16_f32 v1, v1, s0
	global_store_short v[4:5], v1, off
	v_mul_f32_e32 v6, v11, v2
	v_mul_f32_e32 v6, v48, v6
	s_waitcnt vmcnt(7)
	v_lshlrev_b32_e32 v1, 16, v161
	v_mul_f32_e32 v6, v6, v1
	v_mul_f32_e32 v1, 0xbfb8aa3b, v1
	v_exp_f32_e32 v1, v1
	s_nop 0
	v_add_f32_e32 v1, 1.0, v1
	v_rcp_f32_e32 v1, v1
	s_nop 0
	v_mul_f32_e32 v1, v6, v1
	v_cvt_pk_bf16_f32 v1, v1, s0
	global_store_short v[4:5], v1, off offset:32
	v_mul_f32_e32 v6, v15, v2
	v_mul_f32_e32 v6, v47, v6
	s_waitcnt vmcnt(7)
	v_lshlrev_b32_e32 v1, 16, v162
	v_mul_f32_e32 v6, v6, v1
	v_mul_f32_e32 v1, 0xbfb8aa3b, v1
	v_exp_f32_e32 v1, v1
	s_nop 0
	v_add_f32_e32 v1, 1.0, v1
	v_rcp_f32_e32 v1, v1
	s_nop 0
	v_mul_f32_e32 v1, v6, v1
	v_cvt_pk_bf16_f32 v1, v1, s0
	global_store_short v[4:5], v1, off offset:64
	v_mul_f32_e32 v6, v23, v2
	v_mul_f32_e32 v6, v46, v6
	s_waitcnt vmcnt(7)
	v_lshlrev_b32_e32 v1, 16, v163
	v_mul_f32_e32 v6, v6, v1
	v_mul_f32_e32 v1, 0xbfb8aa3b, v1
	v_exp_f32_e32 v1, v1
	s_nop 0
	v_add_f32_e32 v1, 1.0, v1
	v_rcp_f32_e32 v1, v1
	s_nop 0
	v_mul_f32_e32 v1, v6, v1
	v_cvt_pk_bf16_f32 v1, v1, s0
	global_store_short v[4:5], v1, off offset:96
	v_mul_f32_e32 v6, v27, v2
	v_mul_f32_e32 v6, v45, v6
	s_waitcnt vmcnt(7)
	v_lshlrev_b32_e32 v1, 16, v164
	v_mul_f32_e32 v6, v6, v1
	v_mul_f32_e32 v1, 0xbfb8aa3b, v1
	v_exp_f32_e32 v1, v1
	s_nop 0
	v_add_f32_e32 v1, 1.0, v1
	v_rcp_f32_e32 v1, v1
	s_nop 0
	v_mul_f32_e32 v1, v6, v1
	v_cvt_pk_bf16_f32 v1, v1, s0
	global_store_short v[4:5], v1, off offset:128
	v_mul_f32_e32 v6, v31, v2
	v_mul_f32_e32 v6, v43, v6
	s_waitcnt vmcnt(7)
	v_lshlrev_b32_e32 v1, 16, v165
	v_mul_f32_e32 v6, v6, v1
	v_mul_f32_e32 v1, 0xbfb8aa3b, v1
	v_exp_f32_e32 v1, v1
	s_nop 0
	v_add_f32_e32 v1, 1.0, v1
	v_rcp_f32_e32 v1, v1
	s_nop 0
	v_mul_f32_e32 v1, v6, v1
	v_cvt_pk_bf16_f32 v1, v1, s0
	global_store_short v[4:5], v1, off offset:160
	v_mul_f32_e32 v6, v35, v2
	v_mul_f32_e32 v6, v42, v6
	v_mul_f32_e32 v2, v19, v2
	v_mul_f32_e32 v2, v41, v2
	s_waitcnt vmcnt(7)
	v_lshlrev_b32_e32 v1, 16, v166
	v_mul_f32_e32 v6, v6, v1
	v_mul_f32_e32 v1, 0xbfb8aa3b, v1
	v_exp_f32_e32 v1, v1
	s_nop 0
	v_add_f32_e32 v1, 1.0, v1
	v_rcp_f32_e32 v1, v1
	s_nop 0
	v_mul_f32_e32 v1, v6, v1
	v_cvt_pk_bf16_f32 v1, v1, s0
	global_store_short v[4:5], v1, off offset:192
	s_waitcnt vmcnt(7)
	v_lshlrev_b32_e32 v1, 16, v167
	v_mul_f32_e32 v2, v2, v1
	v_mul_f32_e32 v1, 0xbfb8aa3b, v1
	v_exp_f32_e32 v1, v1
	s_nop 0
	v_add_f32_e32 v1, 1.0, v1
	v_rcp_f32_e32 v1, v1
	s_nop 0
	v_mul_f32_e32 v1, v2, v1
	v_cvt_pk_bf16_f32 v1, v1, s0
	global_store_short v[4:5], v1, off offset:224
	s_branch .LBB0_1841

; DI int TID512() { int t = threadIdx.x; asm volatile("" : "+v"(t)); return t; }
; DI void img_load_bf16(const u16* src, int ld, char* smem, int nrows, int rowoff) {
;   for (int slot = TID512(); slot < nrows * 32; slot += 512) {
;     const int row = slot >> 5, c16 = slot & 31;
;     *(u32x4*)(smem + (row + rowoff) * (IMG_LD * 2) + c16 * 16) = __builtin_nontemporal_load((const u32x4*)(src + (size_t)row * ld + c16 * 8));
;   }
; }
; DI void gate_tile(const Params& p, int l, int mt, int nt, char* smem) {
;     ...
;   u16* Y = (u16*)(p.ws + O_YP) + (size_t)row0 * 3072 + col0;
;   const float* bm = p.in[26] + (size_t)l * 3072 + col0 + wc * 64 + fr;
;   img_load_bf16(Y, 3072, smem, 256, 0);
.LBB0_2029:
	v_ashrrev_i32_e32 v138, 5, v133
	v_mad_i64_i32 v[134:135], s[24:25], v138, s97, v[0:1]
	v_mad_u64_u32 v[138:139], s[24:25], v138, s3, v[2:3]
	s_lshl_b32 s34, s97, 4
	s_mov_b32 s35, 0
	s_lshl_b32 s32, s3, 4
	global_load_dwordx4 v[140:143], v[134:135], off nt
	v_lshl_add_u64 v[134:135], v[134:135], 0, s[34:35]
	global_load_dwordx4 v[144:147], v[134:135], off nt
	v_lshl_add_u64 v[134:135], v[134:135], 0, s[34:35]
	global_load_dwordx4 v[148:151], v[134:135], off nt
	v_lshl_add_u64 v[134:135], v[134:135], 0, s[34:35]
	global_load_dwordx4 v[152:155], v[134:135], off nt
	v_lshl_add_u64 v[134:135], v[134:135], 0, s[34:35]
	global_load_dwordx4 v[156:159], v[134:135], off nt
	v_lshl_add_u64 v[134:135], v[134:135], 0, s[34:35]
	global_load_dwordx4 v[160:163], v[134:135], off nt
	v_lshl_add_u64 v[134:135], v[134:135], 0, s[34:35]
	global_load_dwordx4 v[164:167], v[134:135], off nt
	v_lshl_add_u64 v[134:135], v[134:135], 0, s[34:35]
	global_load_dwordx4 v[168:171], v[134:135], off nt
	v_lshl_add_u64 v[134:135], v[134:135], 0, s[34:35]
	global_load_dwordx4 v[176:179], v[134:135], off nt
	v_lshl_add_u64 v[134:135], v[134:135], 0, s[34:35]
	global_load_dwordx4 v[180:183], v[134:135], off nt
	v_lshl_add_u64 v[134:135], v[134:135], 0, s[34:35]
	global_load_dwordx4 v[198:201], v[134:135], off nt
	v_lshl_add_u64 v[134:135], v[134:135], 0, s[34:35]
	global_load_dwordx4 v[202:205], v[134:135], off nt
	v_lshl_add_u64 v[134:135], v[134:135], 0, s[34:35]
	global_load_dwordx4 v[206:209], v[134:135], off nt
	v_lshl_add_u64 v[134:135], v[134:135], 0, s[34:35]
	global_load_dwordx4 v[214:217], v[134:135], off nt
	v_lshl_add_u64 v[134:135], v[134:135], 0, s[34:35]
	global_load_dwordx4 v[218:221], v[134:135], off nt
	v_lshl_add_u64 v[134:135], v[134:135], 0, s[34:35]
	global_load_dwordx4 v[222:225], v[134:135], off nt
	v_lshl_add_u64 v[134:135], v[134:135], 0, s[34:35]
	s_waitcnt vmcnt(15)
	ds_write_b128 v138, v[140:143]
	v_add_u32_e32 v138, s32, v138
	s_waitcnt vmcnt(14)
	ds_write_b128 v138, v[144:147]
	v_add_u32_e32 v138, s32, v138
	s_waitcnt vmcnt(13)
	ds_write_b128 v138, v[148:151]
	v_add_u32_e32 v138, s32, v138
	s_waitcnt vmcnt(12)
	ds_write_b128 v138, v[152:155]
	v_add_u32_e32 v138, s32, v138
	s_waitcnt vmcnt(11)
	ds_write_b128 v138, v[156:159]
	v_add_u32_e32 v138, s32, v138
	s_waitcnt vmcnt(10)
	ds_write_b128 v138, v[160:163]
	v_add_u32_e32 v138, s32, v138
	s_waitcnt vmcnt(9)
	ds_write_b128 v138, v[164:167]
	v_add_u32_e32 v138, s32, v138
	s_waitcnt vmcnt(8)
	ds_write_b128 v138, v[168:171]
	v_add_u32_e32 v138, s32, v138
	s_waitcnt vmcnt(7)
	ds_write_b128 v138, v[176:179]
	v_add_u32_e32 v138, s32, v138
	s_waitcnt vmcnt(6)
	ds_write_b128 v138, v[180:183]
	v_add_u32_e32 v138, s32, v138
	s_waitcnt vmcnt(5)
	ds_write_b128 v138, v[198:201]
	v_add_u32_e32 v138, s32, v138
	s_waitcnt vmcnt(4)
	ds_write_b128 v138, v[202:205]
	v_add_u32_e32 v138, s32, v138
	s_waitcnt vmcnt(3)
	ds_write_b128 v138, v[206:209]
	v_add_u32_e32 v138, s32, v138
	s_waitcnt vmcnt(2)
	ds_write_b128 v138, v[214:217]
	v_add_u32_e32 v138, s32, v138
	s_waitcnt vmcnt(1)
	ds_write_b128 v138, v[218:221]
	v_add_u32_e32 v138, s32, v138
	s_waitcnt vmcnt(0)
	ds_write_b128 v138, v[222:225]
	v_add_u32_e32 v138, s32, v138
	s_branch .LBB0_2020

; DI int TID512() { int t = threadIdx.x; asm volatile("" : "+v"(t)); return t; }
; DI void img_barrier() { asm volatile("s_waitcnt lgkmcnt(0)" ::: "memory"); __builtin_amdgcn_s_barrier(); }
; template <bool ADD>
; DI void imgf_store(float* dst, const float* rsrc, int ld, const char* smem) {
;   const int tid = TID512();
;   const unsigned o0 = (unsigned)((tid >> 6) * ld + (tid & 63) * 4);
;   const char* src = smem + (tid >> 6) * (IMGF_LD * 4) + (tid & 63) * 16;
; #pragma unroll
;   for (int q = 0; q < 16; ++q) {
;     if ((q & 3) == 0) asm volatile("" ::: "memory");
;     float4 v = *(const float4*)(src + q * 8 * (IMGF_LD * 4));
;     float4* d = (float4*)(dst + (o0 + (unsigned)(q * 8 * ld)));
;     if (ADD) { const f32x4 x = __builtin_nontemporal_load((const f32x4*)(rsrc + (o0 + (unsigned)(q * 8 * ld)))); v.x += x[0]; v.y += x[1]; v.z += x[2]; v.w += x[3]; }
;     if (ADD) *d = v;
;     else __builtin_nontemporal_store(f32x4{v.x, v.y, v.z, v.w}, (f32x4*)d);
;   }
; }
; template <bool ADD, bool ROPE>
; DI void tile_out_f32(const f32x4 (&acc)[8][4], float* dst, int ld, char* smem, int prow0, const float* cosT, const float* rsrc = nullptr) {
;     ...
;   for (int h = 0; h < 2; ++h) {
;     img_barrier();
;     imgf_put<ROPE>(acc, h, smem, prow0, cosT);
;     img_barrier();
;     imgf_store<ADD>(dst + (size_t)h * 128 * ld, ADD ? rsrc + (size_t)h * 128 * ld : nullptr, ld, smem);
;   }
.LBB0_2109:
	s_or_b64 exec, exec, s[8:9]
	s_lshl_b32 s20, s20, 17
	v_mov_b32_e32 v0, v184
	s_xor_b64 s[8:9], s[12:13], -1
	s_waitcnt lgkmcnt(0)
	s_barrier
	s_lshl_b64 s[12:13], s[20:21], 2
	s_add_u32 s26, s5, s12
	v_ashrrev_i32_e32 v1, 6, v0
	v_and_b32_e32 v0, 63, v0
	s_addc_u32 s27, s7, s13
	v_lshlrev_b32_e32 v2, 2, v0
	s_add_u32 s12, s28, s12
	v_lshl_or_b32 v172, v1, 10, v2
	s_addc_u32 s13, s29, s13
	v_lshlrev_b64 v[132:133], 2, v[172:173]
	v_lshl_add_u64 v[140:141], s[26:27], 0, v[132:133]
	v_lshl_add_u64 v[132:133], s[12:13], 0, v[132:133]
	v_mul_lo_u32 v1, v1, s71
	v_lshlrev_b32_e32 v0, 4, v0
	v_add3_u32 v0, 16, v1, v0
	v_add_u32_e32 v1, 0x10400, v0
	s_mov_b64 s[24:25], 0x8000
	global_load_dwordx4 v[144:147], v[132:133], off nt
	v_lshl_add_u64 v[132:133], v[132:133], 0, s[24:25]
	global_load_dwordx4 v[148:151], v[132:133], off nt
	v_lshl_add_u64 v[132:133], v[132:133], 0, s[24:25]
	global_load_dwordx4 v[152:155], v[132:133], off nt
	v_lshl_add_u64 v[132:133], v[132:133], 0, s[24:25]
	global_load_dwordx4 v[156:159], v[132:133], off nt
	v_lshl_add_u64 v[132:133], v[132:133], 0, s[24:25]
	global_load_dwordx4 v[160:163], v[132:133], off nt
	v_lshl_add_u64 v[132:133], v[132:133], 0, s[24:25]
	global_load_dwordx4 v[164:167], v[132:133], off nt
	v_lshl_add_u64 v[132:133], v[132:133], 0, s[24:25]
	global_load_dwordx4 v[168:171], v[132:133], off nt
	v_lshl_add_u64 v[132:133], v[132:133], 0, s[24:25]
	global_load_dwordx4 v[176:179], v[132:133], off nt
	v_lshl_add_u64 v[132:133], v[132:133], 0, s[24:25]
	global_load_dwordx4 v[180:183], v[132:133], off nt
	v_lshl_add_u64 v[132:133], v[132:133], 0, s[24:25]
	global_load_dwordx4 v[198:201], v[132:133], off nt
	v_lshl_add_u64 v[132:133], v[132:133], 0, s[24:25]
	global_load_dwordx4 v[202:205], v[132:133], off nt
	v_lshl_add_u64 v[132:133], v[132:133], 0, s[24:25]
	global_load_dwordx4 v[206:209], v[132:133], off nt
	v_lshl_add_u64 v[132:133], v[132:133], 0, s[24:25]
	global_load_dwordx4 v[214:217], v[132:133], off nt
	v_lshl_add_u64 v[132:133], v[132:133], 0, s[24:25]
	global_load_dwordx4 v[218:221], v[132:133], off nt
	v_lshl_add_u64 v[132:133], v[132:133], 0, s[24:25]
	global_load_dwordx4 v[222:225], v[132:133], off nt
	v_lshl_add_u64 v[132:133], v[132:133], 0, s[24:25]
	global_load_dwordx4 v[226:229], v[132:133], off nt
	ds_read_b128 v[230:233], v0
	ds_read_b128 v[234:237], v0 offset:8320
	ds_read_b128 v[238:241], v0 offset:16640
	ds_read_b128 v[242:245], v0 offset:24960
	s_waitcnt vmcnt(15) lgkmcnt(3)
	v_pk_add_f32 v[144:145], v[230:231], v[144:145]
	v_pk_add_f32 v[146:147], v[232:233], v[146:147]
	global_store_dwordx4 v[140:141], v[144:147], off
	v_lshl_add_u64 v[140:141], v[140:141], 0, s[24:25]
	ds_read_b128 v[230:233], v0 offset:33280
	s_waitcnt vmcnt(15) lgkmcnt(3)
	v_pk_add_f32 v[148:149], v[234:235], v[148:149]
	v_pk_add_f32 v[150:151], v[236:237], v[150:151]
	global_store_dwordx4 v[140:141], v[148:151], off
	v_lshl_add_u64 v[140:141], v[140:141], 0, s[24:25]
	ds_read_b128 v[234:237], v0 offset:41600
	s_waitcnt vmcnt(15) lgkmcnt(3)
	v_pk_add_f32 v[152:153], v[238:239], v[152:153]
	v_pk_add_f32 v[154:155], v[240:241], v[154:155]
	global_store_dwordx4 v[140:141], v[152:155], off
	v_lshl_add_u64 v[140:141], v[140:141], 0, s[24:25]
	ds_read_b128 v[238:241], v0 offset:49920
	s_waitcnt vmcnt(15) lgkmcnt(3)
	v_pk_add_f32 v[156:157], v[242:243], v[156:157]
	v_pk_add_f32 v[158:159], v[244:245], v[158:159]
	global_store_dwordx4 v[140:141], v[156:159], off
	v_lshl_add_u64 v[140:141], v[140:141], 0, s[24:25]
	ds_read_b128 v[242:245], v0 offset:58240
	s_waitcnt vmcnt(15) lgkmcnt(3)
	v_pk_add_f32 v[160:161], v[230:231], v[160:161]
	v_pk_add_f32 v[162:163], v[232:233], v[162:163]
	global_store_dwordx4 v[140:141], v[160:163], off
	v_lshl_add_u64 v[140:141], v[140:141], 0, s[24:25]
	ds_read_b128 v[230:233], v1
	s_waitcnt vmcnt(15) lgkmcnt(3)
	v_pk_add_f32 v[164:165], v[234:235], v[164:165]
	v_pk_add_f32 v[166:167], v[236:237], v[166:167]
	global_store_dwordx4 v[140:141], v[164:167], off
	v_lshl_add_u64 v[140:141], v[140:141], 0, s[24:25]
	ds_read_b128 v[234:237], v1 offset:8320
	s_waitcnt vmcnt(15) lgkmcnt(3)
	v_pk_add_f32 v[168:169], v[238:239], v[168:169]
	v_pk_add_f32 v[170:171], v[240:241], v[170:171]
	global_store_dwordx4 v[140:141], v[168:171], off
	v_lshl_add_u64 v[140:141], v[140:141], 0, s[24:25]
	ds_read_b128 v[238:241], v1 offset:16640
	s_waitcnt vmcnt(15) lgkmcnt(3)
	v_pk_add_f32 v[176:177], v[242:243], v[176:177]
	v_pk_add_f32 v[178:179], v[244:245], v[178:179]
	global_store_dwordx4 v[140:141], v[176:179], off
	v_lshl_add_u64 v[140:141], v[140:141], 0, s[24:25]
	ds_read_b128 v[242:245], v1 offset:24960
	s_waitcnt vmcnt(15) lgkmcnt(3)
	v_pk_add_f32 v[180:181], v[230:231], v[180:181]
	v_pk_add_f32 v[182:183], v[232:233], v[182:183]
	global_store_dwordx4 v[140:141], v[180:183], off
	v_lshl_add_u64 v[140:141], v[140:141], 0, s[24:25]
	ds_read_b128 v[230:233], v1 offset:33280
	s_waitcnt vmcnt(15) lgkmcnt(3)
	v_pk_add_f32 v[198:199], v[234:235], v[198:199]
	v_pk_add_f32 v[200:201], v[236:237], v[200:201]
	global_store_dwordx4 v[140:141], v[198:201], off
	v_lshl_add_u64 v[140:141], v[140:141], 0, s[24:25]
	ds_read_b128 v[234:237], v1 offset:41600
	s_waitcnt vmcnt(15) lgkmcnt(3)
	v_pk_add_f32 v[202:203], v[238:239], v[202:203]
	v_pk_add_f32 v[204:205], v[240:241], v[204:205]
	global_store_dwordx4 v[140:141], v[202:205], off
	v_lshl_add_u64 v[140:141], v[140:141], 0, s[24:25]
	ds_read_b128 v[238:241], v1 offset:49920
	s_waitcnt vmcnt(15) lgkmcnt(3)
	v_pk_add_f32 v[206:207], v[242:243], v[206:207]
	v_pk_add_f32 v[208:209], v[244:245], v[208:209]
	global_store_dwordx4 v[140:141], v[206:209], off
	v_lshl_add_u64 v[140:141], v[140:141], 0, s[24:25]
	ds_read_b128 v[242:245], v1 offset:58240
	s_waitcnt vmcnt(15) lgkmcnt(3)
	v_pk_add_f32 v[214:215], v[230:231], v[214:215]
	v_pk_add_f32 v[216:217], v[232:233], v[216:217]
	global_store_dwordx4 v[140:141], v[214:217], off
	v_lshl_add_u64 v[140:141], v[140:141], 0, s[24:25]
	s_waitcnt vmcnt(15) lgkmcnt(2)
	v_pk_add_f32 v[218:219], v[234:235], v[218:219]
	v_pk_add_f32 v[220:221], v[236:237], v[220:221]
	global_store_dwordx4 v[140:141], v[218:221], off
	v_lshl_add_u64 v[140:141], v[140:141], 0, s[24:25]
	s_waitcnt vmcnt(15) lgkmcnt(1)
	v_pk_add_f32 v[222:223], v[238:239], v[222:223]
	v_pk_add_f32 v[224:225], v[240:241], v[224:225]
	global_store_dwordx4 v[140:141], v[222:225], off
	v_lshl_add_u64 v[140:141], v[140:141], 0, s[24:25]
	s_waitcnt vmcnt(15) lgkmcnt(0)
	v_pk_add_f32 v[226:227], v[242:243], v[226:227]
	v_pk_add_f32 v[228:229], v[244:245], v[228:229]
	global_store_dwordx4 v[140:141], v[226:229], off
	s_mov_b32 s20, 1
	s_and_b64 vcc, exec, s[8:9]
	s_mov_b64 s[12:13], 0
	s_cbranch_vccnz .LBB0_2112

; DI bool xcd_tile(int B, int G, int iter, int MTILES, int NT, int& mt, int& nt) {
;   const int nxb = G >> 3;
;   const int x = B & 7, lb = B >> 3;
;   const int q = MTILES >> 3, r = MTILES & 7;
;   const int mx = q + (x < r ? 1 : 0);
;   const int mbase = x * q + (x < r ? x : r);
;   const int j = lb + iter * nxb;
;   if (j >= mx * NT) return false;
;   const int band = j / (8 * NT);
;   const int rem = j - band * 8 * NT;
;   const int nb = (mx - band * 8) < 8 ? (mx - band * 8) : 8;
;   mt = mbase + band * 8 + rem % nb;
;   nt = rem / nb;
;   return true;
; }
.LBB0_2226:
	s_mul_i32 s6, s12, s33
	s_add_i32 s6, s6, s16
	v_readlane_b32 s7, v253, 53
	s_cmp_lt_i32 s6, s7
	s_cselect_b64 s[4:5], -1, 0
	s_cmp_ge_i32 s6, s7
	s_cbranch_scc1 .LBB0_2228
	s_mul_hi_i32 s7, s6, 0x2e8ba2e9
	s_lshr_b32 s13, s7, 31
	s_ashr_i32 s7, s7, 4
	s_add_i32 s7, s7, s13
	s_lshl_b32 s13, s7, 3
	v_readlane_b32 s20, v253, 52
	s_sub_i32 s20, s20, s13
	s_min_u32 s20, s20, 8
	v_cvt_f32_ubyte0_e32 v0, s20
	v_rcp_iflag_f32_e32 v0, v0
	s_sub_i32 s25, 0, s20
	s_mulk_i32 s7, 0xffa8
	s_add_i32 s7, s7, s6
	v_mul_f32_e32 v0, 0x4f7ffffe, v0
	v_cvt_u32_f32_e32 v0, v0
	s_abs_i32 s24, s7
	v_readlane_b32 s6, v252, 25
	s_add_i32 s6, s6, s13
	v_readfirstlane_b32 s26, v0
	s_mul_i32 s25, s25, s26
	s_mul_hi_u32 s25, s26, s25
	s_add_i32 s26, s26, s25
	s_mul_hi_u32 s25, s24, s26
	s_mul_i32 s26, s25, s20
	s_sub_i32 s24, s24, s26
	s_ashr_i32 s13, s7, 31
	s_add_i32 s26, s25, 1
	s_sub_i32 s27, s24, s20
	s_cmp_ge_u32 s24, s20
	s_cselect_b32 s25, s26, s25
	s_cselect_b32 s24, s27, s24
	s_add_i32 s26, s25, 1
	s_cmp_ge_u32 s24, s20
	s_cselect_b32 s24, s26, s25
	s_xor_b32 s24, s24, s13
	s_sub_i32 s44, s24, s13
	s_mul_i32 s13, s44, s20
	s_sub_i32 s7, s7, s13
	s_lshl_b32 s24, s12, 1
	s_add_i32 s24, s24, s7
	s_and_b32 s24, s24, 7
	s_cmp_eq_u32 s20, 8
	s_cselect_b32 s7, s24, s7
	s_add_i32 s45, s6, s7
	s_mov_b64 s[6:7], -1
	s_and_b64 vcc, exec, s[4:5]
	s_cbranch_vccz .LBB0_2225
	s_branch .LBB0_2229

; DI bool xcd_tile(int B, int G, int iter, int MTILES, int NT, int& mt, int& nt) {
;   const int nxb = G >> 3;
;   const int x = B & 7, lb = B >> 3;
;   const int q = MTILES >> 3, r = MTILES & 7;
;   const int mx = q + (x < r ? 1 : 0);
;   const int mbase = x * q + (x < r ? x : r);
;   const int j = lb + iter * nxb;
;   if (j >= mx * NT) return false;
;   const int band = j / (8 * NT);
;   const int rem = j - band * 8 * NT;
;   const int nb = (mx - band * 8) < 8 ? (mx - band * 8) : 8;
;   mt = mbase + band * 8 + rem % nb;
;   nt = rem / nb;
;   return true;
; }
.LBB0_2357:
	s_mul_i32 s6, s12, s33
	s_add_i32 s6, s6, s16
	v_readlane_b32 s7, v253, 53
	s_cmp_lt_i32 s6, s7
	s_cselect_b64 s[4:5], -1, 0
	s_cmp_ge_i32 s6, s7
	s_cbranch_scc1 .LBB0_2359
	s_mul_hi_i32 s7, s6, 0x2e8ba2e9
	s_lshr_b32 s8, s7, 31
	s_ashr_i32 s7, s7, 4
	s_add_i32 s7, s7, s8
	s_lshl_b32 s8, s7, 3
	v_readlane_b32 s9, v253, 52
	s_sub_i32 s9, s9, s8
	s_min_i32 s9, s9, 8
	s_abs_i32 s13, s9
	v_cvt_f32_u32_e32 v0, s13
	s_sub_i32 s24, 0, s13
	s_mulk_i32 s7, 0xffa8
	s_add_i32 s7, s7, s6
	v_rcp_iflag_f32_e32 v0, v0
	v_readlane_b32 s6, v252, 25
	s_add_i32 s6, s6, s8
	s_abs_i32 s8, s7
	v_mul_f32_e32 v0, 0x4f7ffffe, v0
	v_cvt_u32_f32_e32 v0, v0
	s_xor_b32 s20, s7, s9
	s_ashr_i32 s20, s20, 31
	v_readfirstlane_b32 s25, v0
	s_mul_i32 s24, s24, s25
	s_mul_hi_u32 s24, s25, s24
	s_add_i32 s25, s25, s24
	s_mul_hi_u32 s24, s8, s25
	s_mul_i32 s25, s24, s13
	s_sub_i32 s8, s8, s25
	s_add_i32 s26, s24, 1
	s_sub_i32 s25, s8, s13
	s_cmp_ge_u32 s8, s13
	s_cselect_b32 s24, s26, s24
	s_cselect_b32 s8, s25, s8
	s_add_i32 s25, s24, 1
	s_cmp_ge_u32 s8, s13
	s_cselect_b32 s8, s25, s24
	s_xor_b32 s8, s8, s20
	s_sub_i32 s8, s8, s20
	v_writelane_b32 v255, s8, 6
	s_mul_i32 s8, s8, s9
	s_sub_i32 s7, s7, s8
	s_lshl_b32 s24, s12, 1
	s_add_i32 s24, s24, s7
	s_and_b32 s24, s24, 7
	s_cmp_eq_u32 s9, 8
	s_cselect_b32 s7, s24, s7
	s_add_i32 s6, s6, s7
	v_writelane_b32 v255, s6, 7
	s_mov_b64 s[6:7], -1
	s_and_b64 vcc, exec, s[4:5]
	s_cbranch_vccz .LBB0_2356
	s_branch .LBB0_2360

; DI int TID512() { int t = threadIdx.x; asm volatile("" : "+v"(t)); return t; }
; DI void img_load_bf16(const u16* src, int ld, char* smem, int nrows, int rowoff) {
;   for (int slot = TID512(); slot < nrows * 32; slot += 512) {
;     const int row = slot >> 5, c16 = slot & 31;
;     *(u32x4*)(smem + (row + rowoff) * (IMG_LD * 2) + c16 * 16) = __builtin_nontemporal_load((const u32x4*)(src + (size_t)row * ld + c16 * 8));
;   }
; }
; DI void ffup_tile(const Params& p, int l, int mt, int nt, char* smem) {
;     ...
;     const u16* GUt = (const u16*)(p.ws + O_GU) + (size_t)row0 * DFF + col0;
;     if (row0 >= 2) img_load_bf16(GUt - 2 * DFF, DFF, smem, 258, 0); else img_load_bf16(GUt, DFF, smem, 256, 2);
.LBB0_2501:
	v_ashrrev_i32_e32 v138, 5, v133
	v_mad_i64_i32 v[134:135], s[8:9], v138, s96, v[0:1]
	v_mad_u64_u32 v[138:139], s[8:9], v138, s3, v[2:3]
	s_lshl_b32 s34, s96, 4
	s_mov_b32 s35, 0
	s_lshl_b32 s32, s3, 4
	global_load_dwordx4 v[140:143], v[134:135], off nt
	v_lshl_add_u64 v[134:135], v[134:135], 0, s[34:35]
	global_load_dwordx4 v[144:147], v[134:135], off nt
	v_lshl_add_u64 v[134:135], v[134:135], 0, s[34:35]
	global_load_dwordx4 v[148:151], v[134:135], off nt
	v_lshl_add_u64 v[134:135], v[134:135], 0, s[34:35]
	global_load_dwordx4 v[152:155], v[134:135], off nt
	v_lshl_add_u64 v[134:135], v[134:135], 0, s[34:35]
	global_load_dwordx4 v[156:159], v[134:135], off nt
	v_lshl_add_u64 v[134:135], v[134:135], 0, s[34:35]
	global_load_dwordx4 v[160:163], v[134:135], off nt
	v_lshl_add_u64 v[134:135], v[134:135], 0, s[34:35]
	global_load_dwordx4 v[164:167], v[134:135], off nt
	v_lshl_add_u64 v[134:135], v[134:135], 0, s[34:35]
	global_load_dwordx4 v[168:171], v[134:135], off nt
	v_lshl_add_u64 v[134:135], v[134:135], 0, s[34:35]
	global_load_dwordx4 v[176:179], v[134:135], off nt
	v_lshl_add_u64 v[134:135], v[134:135], 0, s[34:35]
	global_load_dwordx4 v[180:183], v[134:135], off nt
	v_lshl_add_u64 v[134:135], v[134:135], 0, s[34:35]
	global_load_dwordx4 v[198:201], v[134:135], off nt
	v_lshl_add_u64 v[134:135], v[134:135], 0, s[34:35]
	global_load_dwordx4 v[202:205], v[134:135], off nt
	v_lshl_add_u64 v[134:135], v[134:135], 0, s[34:35]
	global_load_dwordx4 v[206:209], v[134:135], off nt
	v_lshl_add_u64 v[134:135], v[134:135], 0, s[34:35]
	global_load_dwordx4 v[214:217], v[134:135], off nt
	v_lshl_add_u64 v[134:135], v[134:135], 0, s[34:35]
	global_load_dwordx4 v[218:221], v[134:135], off nt
	v_lshl_add_u64 v[134:135], v[134:135], 0, s[34:35]
	global_load_dwordx4 v[222:225], v[134:135], off nt
	v_lshl_add_u64 v[134:135], v[134:135], 0, s[34:35]
	v_cmp_gt_i32_e32 vcc, 64, v133
	s_and_saveexec_b64 s[8:9], vcc
	s_cbranch_execz .Lmy_ffup_a
	global_load_dwordx4 v[226:229], v[134:135], off nt
.Lmy_ffup_a:
	s_or_b64 exec, exec, s[8:9]
	s_waitcnt vmcnt(15)
	ds_write_b128 v138, v[140:143]
	v_add_u32_e32 v138, s32, v138
	s_waitcnt vmcnt(14)
	ds_write_b128 v138, v[144:147]
	v_add_u32_e32 v138, s32, v138
	s_waitcnt vmcnt(13)
	ds_write_b128 v138, v[148:151]
	v_add_u32_e32 v138, s32, v138
	s_waitcnt vmcnt(12)
	ds_write_b128 v138, v[152:155]
	v_add_u32_e32 v138, s32, v138
	s_waitcnt vmcnt(11)
	ds_write_b128 v138, v[156:159]
	v_add_u32_e32 v138, s32, v138
	s_waitcnt vmcnt(10)
	ds_write_b128 v138, v[160:163]
	v_add_u32_e32 v138, s32, v138
	s_waitcnt vmcnt(9)
	ds_write_b128 v138, v[164:167]
	v_add_u32_e32 v138, s32, v138
	s_waitcnt vmcnt(8)
	ds_write_b128 v138, v[168:171]
	v_add_u32_e32 v138, s32, v138
	s_waitcnt vmcnt(7)
	ds_write_b128 v138, v[176:179]
	v_add_u32_e32 v138, s32, v138
	s_waitcnt vmcnt(6)
	ds_write_b128 v138, v[180:183]
	v_add_u32_e32 v138, s32, v138
	s_waitcnt vmcnt(5)
	ds_write_b128 v138, v[198:201]
	v_add_u32_e32 v138, s32, v138
	s_waitcnt vmcnt(4)
	ds_write_b128 v138, v[202:205]
	v_add_u32_e32 v138, s32, v138
	s_waitcnt vmcnt(3)
	ds_write_b128 v138, v[206:209]
	v_add_u32_e32 v138, s32, v138
	s_waitcnt vmcnt(2)
	ds_write_b128 v138, v[214:217]
	v_add_u32_e32 v138, s32, v138
	s_waitcnt vmcnt(1)
	ds_write_b128 v138, v[218:221]
	v_add_u32_e32 v138, s32, v138
	s_waitcnt vmcnt(0)
	ds_write_b128 v138, v[222:225]
	v_add_u32_e32 v138, s32, v138
	s_and_saveexec_b64 s[8:9], vcc
	s_cbranch_execz .Lmy_ffup_b
	s_waitcnt vmcnt(0)
	ds_write_b128 v138, v[226:229]
.Lmy_ffup_b:
	s_or_b64 exec, exec, s[8:9]
	s_branch .LBB0_2353

; DI int TID512() { int t = threadIdx.x; asm volatile("" : "+v"(t)); return t; }
; DI void img_barrier() { asm volatile("s_waitcnt lgkmcnt(0)" ::: "memory"); __builtin_amdgcn_s_barrier(); }
; template <bool ADD>
; DI void imgf_store(float* dst, const float* rsrc, int ld, const char* smem) {
;   const int tid = TID512();
;   const unsigned o0 = (unsigned)((tid >> 6) * ld + (tid & 63) * 4);
;   const char* src = smem + (tid >> 6) * (IMGF_LD * 4) + (tid & 63) * 16;
; #pragma unroll
;   for (int q = 0; q < 16; ++q) {
;     if ((q & 3) == 0) asm volatile("" ::: "memory");
;     float4 v = *(const float4*)(src + q * 8 * (IMGF_LD * 4));
;     float4* d = (float4*)(dst + (o0 + (unsigned)(q * 8 * ld)));
;     if (ADD) { const f32x4 x = __builtin_nontemporal_load((const f32x4*)(rsrc + (o0 + (unsigned)(q * 8 * ld)))); v.x += x[0]; v.y += x[1]; v.z += x[2]; v.w += x[3]; }
;     if (ADD) *d = v;
;     else __builtin_nontemporal_store(f32x4{v.x, v.y, v.z, v.w}, (f32x4*)d);
;   }
; }
; template <bool ADD, bool ROPE>
; DI void tile_out_f32(const f32x4 (&acc)[8][4], float* dst, int ld, char* smem, int prow0, const float* cosT, const float* rsrc = nullptr) {
; #pragma unroll 1
;   for (int h = 0; h < 2; ++h) {
;     img_barrier();
;     imgf_put<ROPE>(acc, h, smem, prow0, cosT);
;     img_barrier();
;     imgf_store<ADD>(dst + (size_t)h * 128 * ld, ADD ? rsrc + (size_t)h * 128 * ld : nullptr, ld, smem);
;   }
.LBB0_2581:
	s_or_b64 exec, exec, s[8:9]
	v_mov_b32_e32 v0, v184
	s_waitcnt lgkmcnt(0)
	s_barrier
	s_lshl_b32 s20, s20, 17
	s_xor_b64 s[8:9], s[12:13], -1
	s_lshl_b64 s[12:13], s[20:21], 2
	v_ashrrev_i32_e32 v1, 6, v0
	v_and_b32_e32 v0, 63, v0
	s_add_u32 s12, s5, s12
	v_lshlrev_b32_e32 v2, 2, v0
	s_addc_u32 s13, s7, s13
	v_lshl_or_b32 v172, v1, 10, v2
	v_lshl_add_u64 v[140:141], v[172:173], 2, s[12:13]
	v_mov_b32_e32 v132, v140
	v_mov_b32_e32 v133, v141
	v_mul_lo_u32 v1, v1, s71
	v_lshlrev_b32_e32 v0, 4, v0
	v_add3_u32 v0, 16, v1, v0
	v_add_u32_e32 v1, 0x10400, v0
	s_mov_b64 s[24:25], 0x8000
	global_load_dwordx4 v[144:147], v[132:133], off nt
	v_lshl_add_u64 v[132:133], v[132:133], 0, s[24:25]
	global_load_dwordx4 v[148:151], v[132:133], off nt
	v_lshl_add_u64 v[132:133], v[132:133], 0, s[24:25]
	global_load_dwordx4 v[152:155], v[132:133], off nt
	v_lshl_add_u64 v[132:133], v[132:133], 0, s[24:25]
	global_load_dwordx4 v[156:159], v[132:133], off nt
	v_lshl_add_u64 v[132:133], v[132:133], 0, s[24:25]
	global_load_dwordx4 v[160:163], v[132:133], off nt
	v_lshl_add_u64 v[132:133], v[132:133], 0, s[24:25]
	global_load_dwordx4 v[164:167], v[132:133], off nt
	v_lshl_add_u64 v[132:133], v[132:133], 0, s[24:25]
	global_load_dwordx4 v[168:171], v[132:133], off nt
	v_lshl_add_u64 v[132:133], v[132:133], 0, s[24:25]
	global_load_dwordx4 v[176:179], v[132:133], off nt
	v_lshl_add_u64 v[132:133], v[132:133], 0, s[24:25]
	global_load_dwordx4 v[180:183], v[132:133], off nt
	v_lshl_add_u64 v[132:133], v[132:133], 0, s[24:25]
	global_load_dwordx4 v[198:201], v[132:133], off nt
	v_lshl_add_u64 v[132:133], v[132:133], 0, s[24:25]
	global_load_dwordx4 v[202:205], v[132:133], off nt
	v_lshl_add_u64 v[132:133], v[132:133], 0, s[24:25]
	global_load_dwordx4 v[206:209], v[132:133], off nt
	v_lshl_add_u64 v[132:133], v[132:133], 0, s[24:25]
	global_load_dwordx4 v[214:217], v[132:133], off nt
	v_lshl_add_u64 v[132:133], v[132:133], 0, s[24:25]
	global_load_dwordx4 v[218:221], v[132:133], off nt
	v_lshl_add_u64 v[132:133], v[132:133], 0, s[24:25]
	global_load_dwordx4 v[222:225], v[132:133], off nt
	v_lshl_add_u64 v[132:133], v[132:133], 0, s[24:25]
	global_load_dwordx4 v[226:229], v[132:133], off nt
	ds_read_b128 v[230:233], v0
	ds_read_b128 v[234:237], v0 offset:8320
	ds_read_b128 v[238:241], v0 offset:16640
	ds_read_b128 v[242:245], v0 offset:24960
	s_waitcnt vmcnt(15) lgkmcnt(3)
	v_pk_add_f32 v[144:145], v[230:231], v[144:145]
	v_pk_add_f32 v[146:147], v[232:233], v[146:147]
	global_store_dwordx4 v[140:141], v[144:147], off
	v_lshl_add_u64 v[140:141], v[140:141], 0, s[24:25]
	ds_read_b128 v[230:233], v0 offset:33280
	s_waitcnt vmcnt(15) lgkmcnt(3)
	v_pk_add_f32 v[148:149], v[234:235], v[148:149]
	v_pk_add_f32 v[150:151], v[236:237], v[150:151]
	global_store_dwordx4 v[140:141], v[148:151], off
	v_lshl_add_u64 v[140:141], v[140:141], 0, s[24:25]
	ds_read_b128 v[234:237], v0 offset:41600
	s_waitcnt vmcnt(15) lgkmcnt(3)
	v_pk_add_f32 v[152:153], v[238:239], v[152:153]
	v_pk_add_f32 v[154:155], v[240:241], v[154:155]
	global_store_dwordx4 v[140:141], v[152:155], off
	v_lshl_add_u64 v[140:141], v[140:141], 0, s[24:25]
	ds_read_b128 v[238:241], v0 offset:49920
	s_waitcnt vmcnt(15) lgkmcnt(3)
	v_pk_add_f32 v[156:157], v[242:243], v[156:157]
	v_pk_add_f32 v[158:159], v[244:245], v[158:159]
	global_store_dwordx4 v[140:141], v[156:159], off
	v_lshl_add_u64 v[140:141], v[140:141], 0, s[24:25]
	ds_read_b128 v[242:245], v0 offset:58240
	s_waitcnt vmcnt(15) lgkmcnt(3)
	v_pk_add_f32 v[160:161], v[230:231], v[160:161]
	v_pk_add_f32 v[162:163], v[232:233], v[162:163]
	global_store_dwordx4 v[140:141], v[160:163], off
	v_lshl_add_u64 v[140:141], v[140:141], 0, s[24:25]
	ds_read_b128 v[230:233], v1
	s_waitcnt vmcnt(15) lgkmcnt(3)
	v_pk_add_f32 v[164:165], v[234:235], v[164:165]
	v_pk_add_f32 v[166:167], v[236:237], v[166:167]
	global_store_dwordx4 v[140:141], v[164:167], off
	v_lshl_add_u64 v[140:141], v[140:141], 0, s[24:25]
	ds_read_b128 v[234:237], v1 offset:8320
	s_waitcnt vmcnt(15) lgkmcnt(3)
	v_pk_add_f32 v[168:169], v[238:239], v[168:169]
	v_pk_add_f32 v[170:171], v[240:241], v[170:171]
	global_store_dwordx4 v[140:141], v[168:171], off
	v_lshl_add_u64 v[140:141], v[140:141], 0, s[24:25]
	ds_read_b128 v[238:241], v1 offset:16640
	s_waitcnt vmcnt(15) lgkmcnt(3)
	v_pk_add_f32 v[176:177], v[242:243], v[176:177]
	v_pk_add_f32 v[178:179], v[244:245], v[178:179]
	global_store_dwordx4 v[140:141], v[176:179], off
	v_lshl_add_u64 v[140:141], v[140:141], 0, s[24:25]
	ds_read_b128 v[242:245], v1 offset:24960
	s_waitcnt vmcnt(15) lgkmcnt(3)
	v_pk_add_f32 v[180:181], v[230:231], v[180:181]
	v_pk_add_f32 v[182:183], v[232:233], v[182:183]
	global_store_dwordx4 v[140:141], v[180:183], off
	v_lshl_add_u64 v[140:141], v[140:141], 0, s[24:25]
	ds_read_b128 v[230:233], v1 offset:33280
	s_waitcnt vmcnt(15) lgkmcnt(3)
	v_pk_add_f32 v[198:199], v[234:235], v[198:199]
	v_pk_add_f32 v[200:201], v[236:237], v[200:201]
	global_store_dwordx4 v[140:141], v[198:201], off
	v_lshl_add_u64 v[140:141], v[140:141], 0, s[24:25]
	ds_read_b128 v[234:237], v1 offset:41600
	s_waitcnt vmcnt(15) lgkmcnt(3)
	v_pk_add_f32 v[202:203], v[238:239], v[202:203]
	v_pk_add_f32 v[204:205], v[240:241], v[204:205]
	global_store_dwordx4 v[140:141], v[202:205], off
	v_lshl_add_u64 v[140:141], v[140:141], 0, s[24:25]
	ds_read_b128 v[238:241], v1 offset:49920
	s_waitcnt vmcnt(15) lgkmcnt(3)
	v_pk_add_f32 v[206:207], v[242:243], v[206:207]
	v_pk_add_f32 v[208:209], v[244:245], v[208:209]
	global_store_dwordx4 v[140:141], v[206:209], off
	v_lshl_add_u64 v[140:141], v[140:141], 0, s[24:25]
	ds_read_b128 v[242:245], v1 offset:58240
	s_waitcnt vmcnt(15) lgkmcnt(3)
	v_pk_add_f32 v[214:215], v[230:231], v[214:215]
	v_pk_add_f32 v[216:217], v[232:233], v[216:217]
	global_store_dwordx4 v[140:141], v[214:217], off
	v_lshl_add_u64 v[140:141], v[140:141], 0, s[24:25]
	s_waitcnt vmcnt(15) lgkmcnt(2)
	v_pk_add_f32 v[218:219], v[234:235], v[218:219]
	v_pk_add_f32 v[220:221], v[236:237], v[220:221]
	global_store_dwordx4 v[140:141], v[218:221], off
	v_lshl_add_u64 v[140:141], v[140:141], 0, s[24:25]
	s_waitcnt vmcnt(15) lgkmcnt(1)
	v_pk_add_f32 v[222:223], v[238:239], v[222:223]
	v_pk_add_f32 v[224:225], v[240:241], v[224:225]
	global_store_dwordx4 v[140:141], v[222:225], off
	v_lshl_add_u64 v[140:141], v[140:141], 0, s[24:25]
	s_waitcnt vmcnt(15) lgkmcnt(0)
	v_pk_add_f32 v[226:227], v[242:243], v[226:227]
	v_pk_add_f32 v[228:229], v[244:245], v[228:229]
	global_store_dwordx4 v[140:141], v[226:229], off
	s_mov_b32 s20, 1
	s_and_b64 vcc, exec, s[8:9]
	s_mov_b64 s[12:13], 0
	s_cbranch_vccnz .LBB0_2584
